# v73 + K-loops: priority flip after every 8 MFMAs
# speedup vs baseline: 1.0021x; 1.0021x over previous
; #define PG8_STAGE(bufoff, gbase, voff) do { _Pragma("unroll") for (int _i = 0; _i < 2; ++_i) \
;         __builtin_amdgcn_global_load_lds((const unsigned*)((const char*)(gbase) + (voff)[_i]), (PG8_LAS unsigned*)(lds + (bufoff) + ldsw + _i * 8192), 16, 0, 0); } while (0)
; #define PG8_LDA(dst, b, h) do { _Pragma("unroll") for (int m = 0; m < 4; ++m) _Pragma("unroll") for (int k = 0; k < 2; ++k) dst[m][k] = *(const PG8_LAS bf16x8*)(lds + PG8_SA(b, h) + aoff + m * 2048 + k * 1024); } while (0)
; #define PG8_LDB(dst, b, h) do { _Pragma("unroll") for (int n = 0; n < 2; ++n) _Pragma("unroll") for (int k = 0; k < 2; ++k) dst[n][k] = *(const PG8_LAS bf16x8*)(lds + PG8_SB(b, h) + boff + n * 2048 + k * 1024); } while (0)
; #define PG8_MMA(ai, bj, At, Bt) do { __builtin_amdgcn_s_setprio(1); _Pragma("unroll") for (int m = 0; m < 4; ++m) _Pragma("unroll") for (int n = 0; n < 2; ++n) _Pragma("unroll") for (int k = 0; k < 2; ++k) \
;         acc[ai][bj][m][n] = __builtin_amdgcn_mfma_f32_16x16x32_bf16(Bt[n][k], At[m][k], acc[ai][bj][m][n], 0, 0, 0); __builtin_amdgcn_s_setprio(0); } while (0)
; #define PG8_WAIT_V(n) asm volatile("s_waitcnt vmcnt(" #n ")" ::: "memory")
; #define PG8_BAR __builtin_amdgcn_s_barrier()
; template <class Epi, class Sched, bool ALIGN_EPI = false, bool SP2 = false>
; __device__ __forceinline__ void gemm_phase(PG8_LAS unsigned char* lds, const Gemm g, const Sched& S, const Epi& E) {
;     ...
;         for (int t = 0; t < nt; t += 2) {
;             const bool last = (t == nt - 2);
;             const char* a1 = cA + (size_t)(t + 1) * kstep;
;             const char* a2 = last ? nA : cA + (size_t)(t + 2) * kstep; const char* b2 = last ? nB : cB + (size_t)(t + 2) * kstep;
;             const char* a3 = a2 + kstep; const char* b3 = b2 + kstep;
;             if (last && has_next) S.a_ready(nxt);
;             if constexpr (SP2) {
;             PG8_LDB(B0, 0, 0); PG8_LDB(B1, 0, 1); PG8_SCHED; PG8_LDA(At, 0, 0); PG8_STAGE(PG8_SA(1, 1), a1 + hstep, voffA);
;             PG8_WAIT_V(8); PG8_WAIT_L(0); PG8_BAR; PG8_MMA(0, 0, At, B0); PG8_MMA(0, 1, At, B1); PG8_BAR; PG8_SCHED;
;             PG8_LDA(At, 0, 1); PG8_STAGE(PG8_SB(0, 0), b2, voffB); PG8_STAGE(PG8_SB(0, 1), b2 + hstep, voffB); PG8_STAGE(PG8_SA(0, 0), a2, voffA);
;             PG8_WAIT_V(8); PG8_WAIT_L(0); PG8_BAR; PG8_MMA(1, 0, At, B0); PG8_MMA(1, 1, At, B1); PG8_BAR; PG8_SCHED;
.LBB0_100:
	s_add_u32 s28, s8, 0xfffc0080
	s_addc_u32 s29, s9, -1
	s_add_i32 s53, 0, 0x10000
	s_cmp_eq_u32 s45, 12
	s_cselect_b32 s31, s3, s29
	s_cselect_b32 s30, s7, s28
	s_cselect_b32 s29, s11, s44
	s_cselect_b32 s28, s21, s23
	s_add_i32 s56, 0, 0x14000
	v_add_u32_e32 v144, s53, v204
	v_add_u32_e32 v160, s56, v204
	ds_read_b128 v[132:135], v144
	ds_read_b128 v[136:139], v144 offset:1024
	ds_read_b128 v[140:143], v144 offset:2048
	ds_read_b128 v[144:147], v144 offset:3072
	ds_read_b128 v[148:151], v160
	ds_read_b128 v[152:155], v160 offset:1024
	ds_read_b128 v[156:159], v160 offset:2048
	ds_read_b128 v[160:163], v160 offset:3072
	v_lshl_add_u64 v[194:195], s[8:9], 0, v[178:179]
	s_add_i32 m0, s42, 0xc000
	ds_read_b128 v[164:167], v205
	ds_read_b128 v[182:185], v205 offset:1024
	ds_read_b128 v[186:189], v205 offset:2048
	ds_read_b128 v[190:193], v205 offset:3072
	ds_read_b128 v[208:211], v205 offset:4096
	ds_read_b128 v[212:215], v205 offset:5120
	ds_read_b128 v[216:219], v205 offset:6144
	ds_read_b128 v[220:223], v205 offset:7168
	global_load_lds_dwordx4 v[194:195], off
	s_add_i32 m0, s42, 0xe000
	v_lshl_add_u64 v[194:195], s[8:9], 0, v[180:181]
	global_load_lds_dwordx4 v[194:195], off
	s_waitcnt vmcnt(8) lgkmcnt(0)
	s_barrier
	s_setprio 1
	v_mfma_f32_16x16x32_bf16 v[128:131], v[132:135], v[164:167], v[128:131]
	v_mfma_f32_16x16x32_bf16 v[124:127], v[140:143], v[164:167], v[124:127]
	v_mfma_f32_16x16x32_bf16 v[112:115], v[132:135], v[186:189], v[112:115]
	v_mfma_f32_16x16x32_bf16 v[108:111], v[140:143], v[186:189], v[108:111]
	v_mfma_f32_16x16x32_bf16 v[96:99], v[132:135], v[208:211], v[96:99]
	v_mfma_f32_16x16x32_bf16 v[92:95], v[140:143], v[208:211], v[92:95]
	v_mfma_f32_16x16x32_bf16 v[80:83], v[132:135], v[216:219], v[80:83]
	v_mfma_f32_16x16x32_bf16 v[76:79], v[140:143], v[216:219], v[76:79]
	s_setprio 0
	s_setprio 1
	v_mfma_f32_16x16x32_bf16 v[128:131], v[136:139], v[182:185], v[128:131]
	v_mfma_f32_16x16x32_bf16 v[124:127], v[144:147], v[182:185], v[124:127]
	v_mfma_f32_16x16x32_bf16 v[112:115], v[136:139], v[190:193], v[112:115]
	v_mfma_f32_16x16x32_bf16 v[108:111], v[144:147], v[190:193], v[108:111]
	v_mfma_f32_16x16x32_bf16 v[96:99], v[136:139], v[212:215], v[96:99]
	v_mfma_f32_16x16x32_bf16 v[92:95], v[144:147], v[212:215], v[92:95]
	v_mfma_f32_16x16x32_bf16 v[80:83], v[136:139], v[220:223], v[80:83]
	v_mfma_f32_16x16x32_bf16 v[76:79], v[144:147], v[220:223], v[76:79]
	s_setprio 0
	s_setprio 1
	v_mfma_f32_16x16x32_bf16 v[120:123], v[148:151], v[164:167], v[120:123]
	v_mfma_f32_16x16x32_bf16 v[116:119], v[156:159], v[164:167], v[116:119]
	v_mfma_f32_16x16x32_bf16 v[104:107], v[148:151], v[186:189], v[104:107]
	v_mfma_f32_16x16x32_bf16 v[100:103], v[156:159], v[186:189], v[100:103]
	v_mfma_f32_16x16x32_bf16 v[88:91], v[148:151], v[208:211], v[88:91]
	v_mfma_f32_16x16x32_bf16 v[84:87], v[156:159], v[208:211], v[84:87]
	v_mfma_f32_16x16x32_bf16 v[72:75], v[148:151], v[216:219], v[72:75]
	v_mfma_f32_16x16x32_bf16 v[68:71], v[156:159], v[216:219], v[68:71]
	s_setprio 0
	s_setprio 1
	v_mfma_f32_16x16x32_bf16 v[120:123], v[152:155], v[182:185], v[120:123]
	v_mfma_f32_16x16x32_bf16 v[116:119], v[160:163], v[182:185], v[116:119]
	v_mfma_f32_16x16x32_bf16 v[104:107], v[152:155], v[190:193], v[104:107]
	v_mfma_f32_16x16x32_bf16 v[100:103], v[160:163], v[190:193], v[100:103]
	v_mfma_f32_16x16x32_bf16 v[88:91], v[152:155], v[212:215], v[88:91]
	v_mfma_f32_16x16x32_bf16 v[84:87], v[160:163], v[212:215], v[84:87]
	v_mfma_f32_16x16x32_bf16 v[72:75], v[152:155], v[220:223], v[72:75]
	v_mfma_f32_16x16x32_bf16 v[68:71], v[160:163], v[220:223], v[68:71]
	s_setprio 0
	s_barrier
	s_add_i32 s53, s53, s41
	v_lshl_add_u64 v[194:195], s[28:29], 0, v[168:169]
	s_mov_b32 m0, s53
	ds_read_b128 v[164:167], v205 offset:16384
	ds_read_b128 v[182:185], v205 offset:17408
	ds_read_b128 v[186:189], v205 offset:18432
	ds_read_b128 v[190:193], v205 offset:19456
	ds_read_b128 v[208:211], v205 offset:20480
	ds_read_b128 v[212:215], v205 offset:21504
	ds_read_b128 v[216:219], v205 offset:22528
	ds_read_b128 v[220:223], v205 offset:23552
	global_load_lds_dwordx4 v[194:195], off
	s_add_i32 m0, s53, 0x2000
	s_add_u32 s54, s28, 0x40000
	v_lshl_add_u64 v[202:203], s[28:29], 0, v[172:173]
	s_addc_u32 s55, s29, 0
	s_add_i32 s53, s56, s41
	global_load_lds_dwordx4 v[202:203], off
	v_lshl_add_u64 v[224:225], s[54:55], 0, v[168:169]
	s_mov_b32 m0, s53
	v_lshl_add_u64 v[226:227], s[30:31], 0, v[170:171]
	global_load_lds_dwordx4 v[224:225], off
	s_add_i32 m0, s53, 0x2000
	v_lshl_add_u64 v[224:225], s[54:55], 0, v[172:173]
	global_load_lds_dwordx4 v[224:225], off
	s_mov_b32 m0, s42
	v_lshl_add_u64 v[224:225], s[30:31], 0, v[0:1]
	global_load_lds_dwordx4 v[224:225], off
	s_mov_b32 m0, s43
	s_add_i32 s53, 0, 0x18000
	global_load_lds_dwordx4 v[226:227], off
	s_waitcnt vmcnt(8) lgkmcnt(0)
	s_barrier
; #define PG8_STAGE(bufoff, gbase, voff) do { _Pragma("unroll") for (int _i = 0; _i < 2; ++_i) \
;         __builtin_amdgcn_global_load_lds((const unsigned*)((const char*)(gbase) + (voff)[_i]), (PG8_LAS unsigned*)(lds + (bufoff) + ldsw + _i * 8192), 16, 0, 0); } while (0)
; #define PG8_LDA(dst, b, h) do { _Pragma("unroll") for (int m = 0; m < 4; ++m) _Pragma("unroll") for (int k = 0; k < 2; ++k) dst[m][k] = *(const PG8_LAS bf16x8*)(lds + PG8_SA(b, h) + aoff + m * 2048 + k * 1024); } while (0)
; #define PG8_LDB(dst, b, h) do { _Pragma("unroll") for (int n = 0; n < 2; ++n) _Pragma("unroll") for (int k = 0; k < 2; ++k) dst[n][k] = *(const PG8_LAS bf16x8*)(lds + PG8_SB(b, h) + boff + n * 2048 + k * 1024); } while (0)
; #define PG8_MMA(ai, bj, At, Bt) do { __builtin_amdgcn_s_setprio(1); _Pragma("unroll") for (int m = 0; m < 4; ++m) _Pragma("unroll") for (int n = 0; n < 2; ++n) _Pragma("unroll") for (int k = 0; k < 2; ++k) \
;         acc[ai][bj][m][n] = __builtin_amdgcn_mfma_f32_16x16x32_bf16(Bt[n][k], At[m][k], acc[ai][bj][m][n], 0, 0, 0); __builtin_amdgcn_s_setprio(0); } while (0)
; #define PG8_WAIT_V(n) asm volatile("s_waitcnt vmcnt(" #n ")" ::: "memory")
; #define PG8_WAIT_L(n) asm volatile("s_waitcnt lgkmcnt(" #n ")" ::: "memory")
; #define PG8_BAR __builtin_amdgcn_s_barrier()
; #define PG8_SCHED __builtin_amdgcn_sched_barrier(0)
; template <class Epi, class Sched, bool ALIGN_EPI = false, bool SP2 = false>
; __device__ __forceinline__ void gemm_phase(PG8_LAS unsigned char* lds, const Gemm g, const Sched& S, const Epi& E) {
;     ...
;             PG8_WAIT_V(8); PG8_WAIT_L(0); PG8_BAR; PG8_MMA(1, 0, At, B0); PG8_MMA(1, 1, At, B1); PG8_BAR; PG8_SCHED;
;             PG8_LDB(B0, 1, 0); PG8_LDB(B1, 1, 1); PG8_SCHED; PG8_LDA(At, 1, 0); PG8_STAGE(PG8_SA(0, 1), a2 + hstep, voffA);
;             PG8_WAIT_V(8); PG8_WAIT_L(0); PG8_BAR; PG8_MMA(0, 0, At, B0); PG8_MMA(0, 1, At, B1); PG8_BAR; PG8_SCHED;
	s_setprio 1
	v_mfma_f32_16x16x32_bf16 v[64:67], v[132:135], v[164:167], v[64:67]
	v_mfma_f32_16x16x32_bf16 v[60:63], v[140:143], v[164:167], v[60:63]
	v_mfma_f32_16x16x32_bf16 v[48:51], v[132:135], v[186:189], v[48:51]
	v_mfma_f32_16x16x32_bf16 v[44:47], v[140:143], v[186:189], v[44:47]
	v_mfma_f32_16x16x32_bf16 v[32:35], v[132:135], v[208:211], v[32:35]
	v_mfma_f32_16x16x32_bf16 v[28:31], v[140:143], v[208:211], v[28:31]
	v_mfma_f32_16x16x32_bf16 v[16:19], v[132:135], v[216:219], v[16:19]
	v_mfma_f32_16x16x32_bf16 v[12:15], v[140:143], v[216:219], v[12:15]
	s_setprio 0
	s_setprio 1
	v_mfma_f32_16x16x32_bf16 v[64:67], v[136:139], v[182:185], v[64:67]
	v_mfma_f32_16x16x32_bf16 v[60:63], v[144:147], v[182:185], v[60:63]
	v_mfma_f32_16x16x32_bf16 v[48:51], v[136:139], v[190:193], v[48:51]
	v_mfma_f32_16x16x32_bf16 v[44:47], v[144:147], v[190:193], v[44:47]
	v_mfma_f32_16x16x32_bf16 v[32:35], v[136:139], v[212:215], v[32:35]
	v_mfma_f32_16x16x32_bf16 v[28:31], v[144:147], v[212:215], v[28:31]
	v_mfma_f32_16x16x32_bf16 v[16:19], v[136:139], v[220:223], v[16:19]
	v_mfma_f32_16x16x32_bf16 v[12:15], v[144:147], v[220:223], v[12:15]
	s_setprio 0
	s_setprio 1
	v_mfma_f32_16x16x32_bf16 v[56:59], v[148:151], v[164:167], v[56:59]
	v_mfma_f32_16x16x32_bf16 v[52:55], v[156:159], v[164:167], v[52:55]
	v_mfma_f32_16x16x32_bf16 v[40:43], v[148:151], v[186:189], v[40:43]
	v_mfma_f32_16x16x32_bf16 v[36:39], v[156:159], v[186:189], v[36:39]
	v_mfma_f32_16x16x32_bf16 v[24:27], v[148:151], v[208:211], v[24:27]
	v_mfma_f32_16x16x32_bf16 v[20:23], v[156:159], v[208:211], v[20:23]
	v_mfma_f32_16x16x32_bf16 v[8:11], v[148:151], v[216:219], v[8:11]
	v_mfma_f32_16x16x32_bf16 v[4:7], v[156:159], v[216:219], v[4:7]
	s_setprio 0
	s_setprio 1
	v_mfma_f32_16x16x32_bf16 v[56:59], v[152:155], v[182:185], v[56:59]
	v_mfma_f32_16x16x32_bf16 v[52:55], v[160:163], v[182:185], v[52:55]
	v_mfma_f32_16x16x32_bf16 v[40:43], v[152:155], v[190:193], v[40:43]
	v_mfma_f32_16x16x32_bf16 v[36:39], v[160:163], v[190:193], v[36:39]
	v_mfma_f32_16x16x32_bf16 v[24:27], v[152:155], v[212:215], v[24:27]
	v_mfma_f32_16x16x32_bf16 v[20:23], v[160:163], v[212:215], v[20:23]
	v_mfma_f32_16x16x32_bf16 v[8:11], v[152:155], v[220:223], v[8:11]
	v_mfma_f32_16x16x32_bf16 v[4:7], v[160:163], v[220:223], v[4:7]
	s_setprio 0
	s_barrier
	s_add_i32 s54, 0, 0x1c000
	v_add_u32_e32 v144, s53, v204
	v_add_u32_e32 v160, s54, v204
	ds_read_b128 v[132:135], v144
	ds_read_b128 v[136:139], v144 offset:1024
	ds_read_b128 v[140:143], v144 offset:2048
	ds_read_b128 v[144:147], v144 offset:3072
	ds_read_b128 v[148:151], v160
	ds_read_b128 v[152:155], v160 offset:1024
	ds_read_b128 v[156:159], v160 offset:2048
	ds_read_b128 v[160:163], v160 offset:3072
	s_add_u32 s30, s30, 0x40000
	s_addc_u32 s31, s31, 0
	s_mov_b32 m0, s46
	v_lshl_add_u64 v[228:229], s[30:31], 0, v[0:1]
	ds_read_b128 v[164:167], v205 offset:32768
	ds_read_b128 v[182:185], v205 offset:33792
	ds_read_b128 v[186:189], v205 offset:34816
	ds_read_b128 v[190:193], v205 offset:35840
	ds_read_b128 v[208:211], v205 offset:36864
	ds_read_b128 v[212:215], v205 offset:37888
	ds_read_b128 v[216:219], v205 offset:38912
	ds_read_b128 v[220:223], v205 offset:39936
	global_load_lds_dwordx4 v[228:229], off
	s_mov_b32 m0, s47
	v_lshl_add_u64 v[228:229], s[30:31], 0, v[170:171]
	global_load_lds_dwordx4 v[228:229], off
	s_waitcnt vmcnt(8) lgkmcnt(0)
	s_barrier
	s_setprio 1
	v_mfma_f32_16x16x32_bf16 v[128:131], v[132:135], v[164:167], v[128:131]
	v_mfma_f32_16x16x32_bf16 v[124:127], v[140:143], v[164:167], v[124:127]
	v_mfma_f32_16x16x32_bf16 v[112:115], v[132:135], v[186:189], v[112:115]
	v_mfma_f32_16x16x32_bf16 v[108:111], v[140:143], v[186:189], v[108:111]
	v_mfma_f32_16x16x32_bf16 v[96:99], v[132:135], v[208:211], v[96:99]
	v_mfma_f32_16x16x32_bf16 v[92:95], v[140:143], v[208:211], v[92:95]
	v_mfma_f32_16x16x32_bf16 v[80:83], v[132:135], v[216:219], v[80:83]
	v_mfma_f32_16x16x32_bf16 v[76:79], v[140:143], v[216:219], v[76:79]
	s_setprio 0
	s_setprio 1
	v_mfma_f32_16x16x32_bf16 v[128:131], v[136:139], v[182:185], v[128:131]
	v_mfma_f32_16x16x32_bf16 v[124:127], v[144:147], v[182:185], v[124:127]
	v_mfma_f32_16x16x32_bf16 v[112:115], v[136:139], v[190:193], v[112:115]
	v_mfma_f32_16x16x32_bf16 v[108:111], v[144:147], v[190:193], v[108:111]
	v_mfma_f32_16x16x32_bf16 v[96:99], v[136:139], v[212:215], v[96:99]
	v_mfma_f32_16x16x32_bf16 v[92:95], v[144:147], v[212:215], v[92:95]
	v_mfma_f32_16x16x32_bf16 v[80:83], v[136:139], v[220:223], v[80:83]
	v_mfma_f32_16x16x32_bf16 v[76:79], v[144:147], v[220:223], v[76:79]
	s_setprio 0
	s_setprio 1
	v_mfma_f32_16x16x32_bf16 v[120:123], v[148:151], v[164:167], v[120:123]
	v_mfma_f32_16x16x32_bf16 v[116:119], v[156:159], v[164:167], v[116:119]
	v_mfma_f32_16x16x32_bf16 v[104:107], v[148:151], v[186:189], v[104:107]
	v_mfma_f32_16x16x32_bf16 v[100:103], v[156:159], v[186:189], v[100:103]
	v_mfma_f32_16x16x32_bf16 v[88:91], v[148:151], v[208:211], v[88:91]
	v_mfma_f32_16x16x32_bf16 v[84:87], v[156:159], v[208:211], v[84:87]
	v_mfma_f32_16x16x32_bf16 v[72:75], v[148:151], v[216:219], v[72:75]
	v_mfma_f32_16x16x32_bf16 v[68:71], v[156:159], v[216:219], v[68:71]
	s_setprio 0
	s_setprio 1
	v_mfma_f32_16x16x32_bf16 v[120:123], v[152:155], v[182:185], v[120:123]
	v_mfma_f32_16x16x32_bf16 v[116:119], v[160:163], v[182:185], v[116:119]
	v_mfma_f32_16x16x32_bf16 v[104:107], v[152:155], v[190:193], v[104:107]
	v_mfma_f32_16x16x32_bf16 v[100:103], v[160:163], v[190:193], v[100:103]
	v_mfma_f32_16x16x32_bf16 v[88:91], v[152:155], v[212:215], v[88:91]
	v_mfma_f32_16x16x32_bf16 v[84:87], v[160:163], v[212:215], v[84:87]
	v_mfma_f32_16x16x32_bf16 v[72:75], v[152:155], v[220:223], v[72:75]
	v_mfma_f32_16x16x32_bf16 v[68:71], v[160:163], v[220:223], v[68:71]
	s_setprio 0
	s_barrier
; #define PG8_STAGE(bufoff, gbase, voff) do { _Pragma("unroll") for (int _i = 0; _i < 2; ++_i) \
;         __builtin_amdgcn_global_load_lds((const unsigned*)((const char*)(gbase) + (voff)[_i]), (PG8_LAS unsigned*)(lds + (bufoff) + ldsw + _i * 8192), 16, 0, 0); } while (0)
; #define PG8_LDA(dst, b, h) do { _Pragma("unroll") for (int m = 0; m < 4; ++m) _Pragma("unroll") for (int k = 0; k < 2; ++k) dst[m][k] = *(const PG8_LAS bf16x8*)(lds + PG8_SA(b, h) + aoff + m * 2048 + k * 1024); } while (0)
; #define PG8_MMA(ai, bj, At, Bt) do { __builtin_amdgcn_s_setprio(1); _Pragma("unroll") for (int m = 0; m < 4; ++m) _Pragma("unroll") for (int n = 0; n < 2; ++n) _Pragma("unroll") for (int k = 0; k < 2; ++k) \
;         acc[ai][bj][m][n] = __builtin_amdgcn_mfma_f32_16x16x32_bf16(Bt[n][k], At[m][k], acc[ai][bj][m][n], 0, 0, 0); __builtin_amdgcn_s_setprio(0); } while (0)
; #define PG8_WAIT_V(n) asm volatile("s_waitcnt vmcnt(" #n ")" ::: "memory")
; #define PG8_WAIT_L(n) asm volatile("s_waitcnt lgkmcnt(" #n ")" ::: "memory")
; #define PG8_BAR __builtin_amdgcn_s_barrier()
; #define PG8_SCHED __builtin_amdgcn_sched_barrier(0)
; template <class Epi, class Sched, bool ALIGN_EPI = false, bool SP2 = false>
; __device__ __forceinline__ void gemm_phase(PG8_LAS unsigned char* lds, const Gemm g, const Sched& S, const Epi& E) {
;     ...
;             PG8_LDA(At, 1, 1); PG8_STAGE(PG8_SB(1, 0), b3, voffB); PG8_STAGE(PG8_SB(1, 1), b3 + hstep, voffB); PG8_STAGE(PG8_SA(1, 0), a3, voffA);
;             PG8_WAIT_V(8); PG8_WAIT_L(0); PG8_BAR; PG8_MMA(1, 0, At, B0); PG8_MMA(1, 1, At, B1); PG8_BAR; PG8_SCHED;
;     ...
;         if constexpr (ALIGN_EPI) { if (wr == 0) PG8_BAR; }
	s_add_i32 s30, s53, s41
	v_lshl_add_u64 v[194:195], v[194:195], 0, s[82:83]
	s_mov_b32 m0, s30
	ds_read_b128 v[164:167], v205 offset:49152
	ds_read_b128 v[182:185], v205 offset:50176
	ds_read_b128 v[186:189], v205 offset:51200
	ds_read_b128 v[190:193], v205 offset:52224
	ds_read_b128 v[208:211], v205 offset:53248
	ds_read_b128 v[212:215], v205 offset:54272
	ds_read_b128 v[216:219], v205 offset:55296
	ds_read_b128 v[220:223], v205 offset:56320
	global_load_lds_dwordx4 v[194:195], off
	s_add_i32 m0, s30, 0x2000
	s_add_u32 s28, s28, 0x40080
	v_lshl_add_u64 v[194:195], v[202:203], 0, s[82:83]
	s_addc_u32 s29, s29, 0
	s_add_i32 s30, s54, s41
	global_load_lds_dwordx4 v[194:195], off
	s_mov_b32 m0, s30
	v_lshl_add_u64 v[194:195], s[28:29], 0, v[168:169]
	global_load_lds_dwordx4 v[194:195], off
	s_add_i32 m0, s30, 0x2000
	v_lshl_add_u64 v[194:195], s[28:29], 0, v[172:173]
	global_load_lds_dwordx4 v[194:195], off
	s_mov_b32 m0, s50
	v_lshl_add_u64 v[194:195], v[224:225], 0, s[82:83]
	global_load_lds_dwordx4 v[194:195], off
	s_mov_b32 m0, s51
	v_lshl_add_u64 v[194:195], v[226:227], 0, s[82:83]
	global_load_lds_dwordx4 v[194:195], off
	s_waitcnt vmcnt(8) lgkmcnt(0)
	s_barrier
	s_setprio 1
	v_mfma_f32_16x16x32_bf16 v[64:67], v[132:135], v[164:167], v[64:67]
	v_mfma_f32_16x16x32_bf16 v[60:63], v[140:143], v[164:167], v[60:63]
	v_mfma_f32_16x16x32_bf16 v[48:51], v[132:135], v[186:189], v[48:51]
	v_mfma_f32_16x16x32_bf16 v[44:47], v[140:143], v[186:189], v[44:47]
	v_mfma_f32_16x16x32_bf16 v[32:35], v[132:135], v[208:211], v[32:35]
	v_mfma_f32_16x16x32_bf16 v[28:31], v[140:143], v[208:211], v[28:31]
	v_mfma_f32_16x16x32_bf16 v[16:19], v[132:135], v[216:219], v[16:19]
	v_mfma_f32_16x16x32_bf16 v[12:15], v[140:143], v[216:219], v[12:15]
	s_setprio 0
	s_setprio 1
	v_mfma_f32_16x16x32_bf16 v[64:67], v[136:139], v[182:185], v[64:67]
	v_mfma_f32_16x16x32_bf16 v[60:63], v[144:147], v[182:185], v[60:63]
	v_mfma_f32_16x16x32_bf16 v[48:51], v[136:139], v[190:193], v[48:51]
	v_mfma_f32_16x16x32_bf16 v[44:47], v[144:147], v[190:193], v[44:47]
	v_mfma_f32_16x16x32_bf16 v[32:35], v[136:139], v[212:215], v[32:35]
	v_mfma_f32_16x16x32_bf16 v[28:31], v[144:147], v[212:215], v[28:31]
	v_mfma_f32_16x16x32_bf16 v[16:19], v[136:139], v[220:223], v[16:19]
	v_mfma_f32_16x16x32_bf16 v[12:15], v[144:147], v[220:223], v[12:15]
	s_setprio 0
	s_setprio 1
	v_mfma_f32_16x16x32_bf16 v[56:59], v[148:151], v[164:167], v[56:59]
	v_mfma_f32_16x16x32_bf16 v[52:55], v[156:159], v[164:167], v[52:55]
	v_mfma_f32_16x16x32_bf16 v[40:43], v[148:151], v[186:189], v[40:43]
	v_mfma_f32_16x16x32_bf16 v[36:39], v[156:159], v[186:189], v[36:39]
	v_mfma_f32_16x16x32_bf16 v[24:27], v[148:151], v[208:211], v[24:27]
	v_mfma_f32_16x16x32_bf16 v[20:23], v[156:159], v[208:211], v[20:23]
	v_mfma_f32_16x16x32_bf16 v[8:11], v[148:151], v[216:219], v[8:11]
	v_mfma_f32_16x16x32_bf16 v[4:7], v[156:159], v[216:219], v[4:7]
	s_setprio 0
	s_setprio 1
	v_mfma_f32_16x16x32_bf16 v[56:59], v[152:155], v[182:185], v[56:59]
	v_mfma_f32_16x16x32_bf16 v[52:55], v[160:163], v[182:185], v[52:55]
	v_mfma_f32_16x16x32_bf16 v[40:43], v[152:155], v[190:193], v[40:43]
	v_mfma_f32_16x16x32_bf16 v[36:39], v[160:163], v[190:193], v[36:39]
	v_mfma_f32_16x16x32_bf16 v[24:27], v[152:155], v[212:215], v[24:27]
	v_mfma_f32_16x16x32_bf16 v[20:23], v[160:163], v[212:215], v[20:23]
	v_mfma_f32_16x16x32_bf16 v[8:11], v[152:155], v[220:223], v[8:11]
	v_mfma_f32_16x16x32_bf16 v[4:7], v[160:163], v[220:223], v[4:7]
	s_setprio 0
	s_barrier
	s_add_i32 s45, s45, 2
	s_add_u32 s8, s8, 0x100
	s_addc_u32 s9, s9, 0
	s_add_u32 s23, s23, 0x100
	s_addc_u32 s44, s44, 0
	s_cmp_gt_u32 s45, 13
	s_cbranch_scc0 .LBB0_100
	s_and_b64 vcc, exec, s[14:15]
	s_cbranch_vccz .LBB0_103
	s_barrier

; #define PG8_STAGE(bufoff, gbase, voff) do { _Pragma("unroll") for (int _i = 0; _i < 2; ++_i) \
;         __builtin_amdgcn_global_load_lds((const unsigned*)((const char*)(gbase) + (voff)[_i]), (PG8_LAS unsigned*)(lds + (bufoff) + ldsw + _i * 8192), 16, 0, 0); } while (0)
; #define PG8_LDA(dst, b, h) do { _Pragma("unroll") for (int m = 0; m < 4; ++m) _Pragma("unroll") for (int k = 0; k < 2; ++k) dst[m][k] = *(const PG8_LAS bf16x8*)(lds + PG8_SA(b, h) + aoff + m * 2048 + k * 1024); } while (0)
; #define PG8_LDB(dst, b, h) do { _Pragma("unroll") for (int n = 0; n < 2; ++n) _Pragma("unroll") for (int k = 0; k < 2; ++k) dst[n][k] = *(const PG8_LAS bf16x8*)(lds + PG8_SB(b, h) + boff + n * 2048 + k * 1024); } while (0)
; #define PG8_MMA(ai, bj, At, Bt) do { __builtin_amdgcn_s_setprio(1); _Pragma("unroll") for (int m = 0; m < 4; ++m) _Pragma("unroll") for (int n = 0; n < 2; ++n) _Pragma("unroll") for (int k = 0; k < 2; ++k) \
;         acc[ai][bj][m][n] = __builtin_amdgcn_mfma_f32_16x16x32_bf16(Bt[n][k], At[m][k], acc[ai][bj][m][n], 0, 0, 0); __builtin_amdgcn_s_setprio(0); } while (0)
; #define PG8_WAIT_V(n) asm volatile("s_waitcnt vmcnt(" #n ")" ::: "memory")
; #define PG8_BAR __builtin_amdgcn_s_barrier()
; template <class Epi, class Sched, bool ALIGN_EPI = false, bool SP2 = false>
; __device__ __forceinline__ void gemm_phase(PG8_LAS unsigned char* lds, const Gemm g, const Sched& S, const Epi& E) {
;     ...
;         for (int t = 0; t < nt; t += 2) {
;             const bool last = (t == nt - 2);
;             const char* a1 = cA + (size_t)(t + 1) * kstep;
;             const char* a2 = last ? nA : cA + (size_t)(t + 2) * kstep; const char* b2 = last ? nB : cB + (size_t)(t + 2) * kstep;
;             const char* a3 = a2 + kstep; const char* b3 = b2 + kstep;
;             if (last && has_next) S.a_ready(nxt);
;             if constexpr (SP2) {
;             PG8_LDB(B0, 0, 0); PG8_LDB(B1, 0, 1); PG8_SCHED; PG8_LDA(At, 0, 0); PG8_STAGE(PG8_SA(1, 1), a1 + hstep, voffA);
;             PG8_WAIT_V(8); PG8_WAIT_L(0); PG8_BAR; PG8_MMA(0, 0, At, B0); PG8_MMA(0, 1, At, B1); PG8_BAR; PG8_SCHED;
;             PG8_LDA(At, 0, 1); PG8_STAGE(PG8_SB(0, 0), b2, voffB); PG8_STAGE(PG8_SB(0, 1), b2 + hstep, voffB); PG8_STAGE(PG8_SA(0, 0), a2, voffA);
;             PG8_WAIT_V(8); PG8_WAIT_L(0); PG8_BAR; PG8_MMA(1, 0, At, B0); PG8_MMA(1, 1, At, B1); PG8_BAR; PG8_SCHED;
.LBB0_329:
	s_add_u32 s30, s28, 0xfffc0080
	s_addc_u32 s31, s29, -1
	s_add_i32 s52, 0, 0x10000
	s_cmp_eq_u32 s45, 12
	s_cselect_b32 s35, s3, s31
	s_cselect_b32 s34, s17, s30
	s_cselect_b32 s31, s19, s44
	s_cselect_b32 s30, s25, s27
	s_add_i32 s54, 0, 0x14000
	v_add_u32_e32 v128, s52, v251
	v_add_u32_e32 v156, s54, v251
	ds_read_b128 v[108:111], v128
	ds_read_b128 v[112:115], v128 offset:1024
	ds_read_b128 v[124:127], v128 offset:2048
	ds_read_b128 v[128:131], v128 offset:3072
	ds_read_b128 v[132:135], v156
	ds_read_b128 v[140:143], v156 offset:1024
	ds_read_b128 v[148:151], v156 offset:2048
	ds_read_b128 v[156:159], v156 offset:3072
	v_lshl_add_u64 v[212:213], s[28:29], 0, v[208:209]
	s_add_i32 m0, s42, 0xc000
	ds_read_b128 v[164:167], v253
	ds_read_b128 v[168:171], v253 offset:1024
	ds_read_b128 v[172:175], v253 offset:2048
	ds_read_b128 v[176:179], v253 offset:3072
	ds_read_b128 v[180:183], v253 offset:4096
	ds_read_b128 v[184:187], v253 offset:5120
	ds_read_b128 v[188:191], v253 offset:6144
	ds_read_b128 v[192:195], v253 offset:7168
	global_load_lds_dwordx4 v[212:213], off
	s_add_i32 m0, s42, 0xe000
	v_lshl_add_u64 v[212:213], s[28:29], 0, v[210:211]
	global_load_lds_dwordx4 v[212:213], off
	s_waitcnt vmcnt(8) lgkmcnt(0)
	s_barrier
	s_setprio 1
	v_mfma_f32_16x16x32_bf16 v[160:163], v[108:111], v[164:167], v[160:163]
	v_mfma_f32_16x16x32_bf16 v[152:155], v[124:127], v[164:167], v[152:155]
	v_mfma_f32_16x16x32_bf16 v[120:123], v[108:111], v[172:175], v[120:123]
	v_mfma_f32_16x16x32_bf16 v[116:119], v[124:127], v[172:175], v[116:119]
	v_mfma_f32_16x16x32_bf16 v[96:99], v[108:111], v[180:183], v[96:99]
	v_mfma_f32_16x16x32_bf16 v[92:95], v[124:127], v[180:183], v[92:95]
	v_mfma_f32_16x16x32_bf16 v[80:83], v[108:111], v[188:191], v[80:83]
	v_mfma_f32_16x16x32_bf16 v[76:79], v[124:127], v[188:191], v[76:79]
	s_setprio 0
	s_setprio 1
	v_mfma_f32_16x16x32_bf16 v[160:163], v[112:115], v[168:171], v[160:163]
	v_mfma_f32_16x16x32_bf16 v[152:155], v[128:131], v[168:171], v[152:155]
	v_mfma_f32_16x16x32_bf16 v[120:123], v[112:115], v[176:179], v[120:123]
	v_mfma_f32_16x16x32_bf16 v[116:119], v[128:131], v[176:179], v[116:119]
	v_mfma_f32_16x16x32_bf16 v[96:99], v[112:115], v[184:187], v[96:99]
	v_mfma_f32_16x16x32_bf16 v[92:95], v[128:131], v[184:187], v[92:95]
	v_mfma_f32_16x16x32_bf16 v[80:83], v[112:115], v[192:195], v[80:83]
	v_mfma_f32_16x16x32_bf16 v[76:79], v[128:131], v[192:195], v[76:79]
	s_setprio 0
	s_setprio 1
	v_mfma_f32_16x16x32_bf16 v[144:147], v[132:135], v[164:167], v[144:147]
	v_mfma_f32_16x16x32_bf16 v[136:139], v[148:151], v[164:167], v[136:139]
	v_mfma_f32_16x16x32_bf16 v[104:107], v[132:135], v[172:175], v[104:107]
	v_mfma_f32_16x16x32_bf16 v[100:103], v[148:151], v[172:175], v[100:103]
	v_mfma_f32_16x16x32_bf16 v[88:91], v[132:135], v[180:183], v[88:91]
	v_mfma_f32_16x16x32_bf16 v[84:87], v[148:151], v[180:183], v[84:87]
	v_mfma_f32_16x16x32_bf16 v[72:75], v[132:135], v[188:191], v[72:75]
	v_mfma_f32_16x16x32_bf16 v[68:71], v[148:151], v[188:191], v[68:71]
	s_setprio 0
	s_setprio 1
	v_mfma_f32_16x16x32_bf16 v[144:147], v[140:143], v[168:171], v[144:147]
	v_mfma_f32_16x16x32_bf16 v[136:139], v[156:159], v[168:171], v[136:139]
	v_mfma_f32_16x16x32_bf16 v[104:107], v[140:143], v[176:179], v[104:107]
	v_mfma_f32_16x16x32_bf16 v[100:103], v[156:159], v[176:179], v[100:103]
	v_mfma_f32_16x16x32_bf16 v[88:91], v[140:143], v[184:187], v[88:91]
	v_mfma_f32_16x16x32_bf16 v[84:87], v[156:159], v[184:187], v[84:87]
	v_mfma_f32_16x16x32_bf16 v[72:75], v[140:143], v[192:195], v[72:75]
	v_mfma_f32_16x16x32_bf16 v[68:71], v[156:159], v[192:195], v[68:71]
	s_setprio 0
	s_barrier
	s_add_i32 s52, s52, s41
	v_lshl_add_u64 v[212:213], s[30:31], 0, v[202:203]
	s_mov_b32 m0, s52
	ds_read_b128 v[164:167], v253 offset:16384
	ds_read_b128 v[168:171], v253 offset:17408
	ds_read_b128 v[172:175], v253 offset:18432
	ds_read_b128 v[176:179], v253 offset:19456
	ds_read_b128 v[180:183], v253 offset:20480
	ds_read_b128 v[184:187], v253 offset:21504
	ds_read_b128 v[188:191], v253 offset:22528
	ds_read_b128 v[192:195], v253 offset:23552
	global_load_lds_dwordx4 v[212:213], off
	s_add_i32 m0, s52, 0x2000
	s_add_u32 s52, s30, 0x40000
	v_lshl_add_u64 v[214:215], s[30:31], 0, v[206:207]
	s_addc_u32 s53, s31, 0
	s_add_i32 s54, s54, s41
	global_load_lds_dwordx4 v[214:215], off
	v_lshl_add_u64 v[216:217], s[52:53], 0, v[202:203]
	s_mov_b32 m0, s54
	v_lshl_add_u64 v[218:219], s[34:35], 0, v[204:205]
	global_load_lds_dwordx4 v[216:217], off
	s_add_i32 m0, s54, 0x2000
	v_lshl_add_u64 v[216:217], s[52:53], 0, v[206:207]
	global_load_lds_dwordx4 v[216:217], off
	s_mov_b32 m0, s42
	v_lshl_add_u64 v[216:217], s[34:35], 0, v[0:1]
	global_load_lds_dwordx4 v[216:217], off
	s_mov_b32 m0, s43
	s_add_i32 s52, 0, 0x18000
	global_load_lds_dwordx4 v[218:219], off
	s_waitcnt vmcnt(8) lgkmcnt(0)
	s_barrier
; #define PG8_STAGE(bufoff, gbase, voff) do { _Pragma("unroll") for (int _i = 0; _i < 2; ++_i) \
;         __builtin_amdgcn_global_load_lds((const unsigned*)((const char*)(gbase) + (voff)[_i]), (PG8_LAS unsigned*)(lds + (bufoff) + ldsw + _i * 8192), 16, 0, 0); } while (0)
; #define PG8_LDA(dst, b, h) do { _Pragma("unroll") for (int m = 0; m < 4; ++m) _Pragma("unroll") for (int k = 0; k < 2; ++k) dst[m][k] = *(const PG8_LAS bf16x8*)(lds + PG8_SA(b, h) + aoff + m * 2048 + k * 1024); } while (0)
; #define PG8_LDB(dst, b, h) do { _Pragma("unroll") for (int n = 0; n < 2; ++n) _Pragma("unroll") for (int k = 0; k < 2; ++k) dst[n][k] = *(const PG8_LAS bf16x8*)(lds + PG8_SB(b, h) + boff + n * 2048 + k * 1024); } while (0)
; #define PG8_MMA(ai, bj, At, Bt) do { __builtin_amdgcn_s_setprio(1); _Pragma("unroll") for (int m = 0; m < 4; ++m) _Pragma("unroll") for (int n = 0; n < 2; ++n) _Pragma("unroll") for (int k = 0; k < 2; ++k) \
;         acc[ai][bj][m][n] = __builtin_amdgcn_mfma_f32_16x16x32_bf16(Bt[n][k], At[m][k], acc[ai][bj][m][n], 0, 0, 0); __builtin_amdgcn_s_setprio(0); } while (0)
; #define PG8_WAIT_V(n) asm volatile("s_waitcnt vmcnt(" #n ")" ::: "memory")
; #define PG8_WAIT_L(n) asm volatile("s_waitcnt lgkmcnt(" #n ")" ::: "memory")
; #define PG8_BAR __builtin_amdgcn_s_barrier()
; #define PG8_SCHED __builtin_amdgcn_sched_barrier(0)
; template <class Epi, class Sched, bool ALIGN_EPI = false, bool SP2 = false>
; __device__ __forceinline__ void gemm_phase(PG8_LAS unsigned char* lds, const Gemm g, const Sched& S, const Epi& E) {
;     ...
;             PG8_WAIT_V(8); PG8_WAIT_L(0); PG8_BAR; PG8_MMA(1, 0, At, B0); PG8_MMA(1, 1, At, B1); PG8_BAR; PG8_SCHED;
;             PG8_LDB(B0, 1, 0); PG8_LDB(B1, 1, 1); PG8_SCHED; PG8_LDA(At, 1, 0); PG8_STAGE(PG8_SA(0, 1), a2 + hstep, voffA);
;             PG8_WAIT_V(8); PG8_WAIT_L(0); PG8_BAR; PG8_MMA(0, 0, At, B0); PG8_MMA(0, 1, At, B1); PG8_BAR; PG8_SCHED;
	s_setprio 1
	v_mfma_f32_16x16x32_bf16 v[64:67], v[108:111], v[164:167], v[64:67]
	v_mfma_f32_16x16x32_bf16 v[60:63], v[124:127], v[164:167], v[60:63]
	v_mfma_f32_16x16x32_bf16 v[48:51], v[108:111], v[172:175], v[48:51]
	v_mfma_f32_16x16x32_bf16 v[44:47], v[124:127], v[172:175], v[44:47]
	v_mfma_f32_16x16x32_bf16 v[32:35], v[108:111], v[180:183], v[32:35]
	v_mfma_f32_16x16x32_bf16 v[28:31], v[124:127], v[180:183], v[28:31]
	v_mfma_f32_16x16x32_bf16 v[16:19], v[108:111], v[188:191], v[16:19]
	v_mfma_f32_16x16x32_bf16 v[12:15], v[124:127], v[188:191], v[12:15]
	s_setprio 0
	s_setprio 1
	v_mfma_f32_16x16x32_bf16 v[64:67], v[112:115], v[168:171], v[64:67]
	v_mfma_f32_16x16x32_bf16 v[60:63], v[128:131], v[168:171], v[60:63]
	v_mfma_f32_16x16x32_bf16 v[48:51], v[112:115], v[176:179], v[48:51]
	v_mfma_f32_16x16x32_bf16 v[44:47], v[128:131], v[176:179], v[44:47]
	v_mfma_f32_16x16x32_bf16 v[32:35], v[112:115], v[184:187], v[32:35]
	v_mfma_f32_16x16x32_bf16 v[28:31], v[128:131], v[184:187], v[28:31]
	v_mfma_f32_16x16x32_bf16 v[16:19], v[112:115], v[192:195], v[16:19]
	v_mfma_f32_16x16x32_bf16 v[12:15], v[128:131], v[192:195], v[12:15]
	s_setprio 0
	s_setprio 1
	v_mfma_f32_16x16x32_bf16 v[56:59], v[132:135], v[164:167], v[56:59]
	v_mfma_f32_16x16x32_bf16 v[52:55], v[148:151], v[164:167], v[52:55]
	v_mfma_f32_16x16x32_bf16 v[40:43], v[132:135], v[172:175], v[40:43]
	v_mfma_f32_16x16x32_bf16 v[36:39], v[148:151], v[172:175], v[36:39]
	v_mfma_f32_16x16x32_bf16 v[24:27], v[132:135], v[180:183], v[24:27]
	v_mfma_f32_16x16x32_bf16 v[20:23], v[148:151], v[180:183], v[20:23]
	v_mfma_f32_16x16x32_bf16 v[8:11], v[132:135], v[188:191], v[8:11]
	v_mfma_f32_16x16x32_bf16 v[4:7], v[148:151], v[188:191], v[4:7]
	s_setprio 0
	s_setprio 1
	v_mfma_f32_16x16x32_bf16 v[56:59], v[140:143], v[168:171], v[56:59]
	v_mfma_f32_16x16x32_bf16 v[52:55], v[156:159], v[168:171], v[52:55]
	v_mfma_f32_16x16x32_bf16 v[40:43], v[140:143], v[176:179], v[40:43]
	v_mfma_f32_16x16x32_bf16 v[36:39], v[156:159], v[176:179], v[36:39]
	v_mfma_f32_16x16x32_bf16 v[24:27], v[140:143], v[184:187], v[24:27]
	v_mfma_f32_16x16x32_bf16 v[20:23], v[156:159], v[184:187], v[20:23]
	v_mfma_f32_16x16x32_bf16 v[8:11], v[140:143], v[192:195], v[8:11]
	v_mfma_f32_16x16x32_bf16 v[4:7], v[156:159], v[192:195], v[4:7]
	s_setprio 0
	s_barrier
	s_add_i32 s53, 0, 0x1c000
	v_add_u32_e32 v128, s52, v251
	v_add_u32_e32 v156, s53, v251
	ds_read_b128 v[108:111], v128
	ds_read_b128 v[112:115], v128 offset:1024
	ds_read_b128 v[124:127], v128 offset:2048
	ds_read_b128 v[128:131], v128 offset:3072
	ds_read_b128 v[132:135], v156
	ds_read_b128 v[140:143], v156 offset:1024
	ds_read_b128 v[148:151], v156 offset:2048
	ds_read_b128 v[156:159], v156 offset:3072
	s_add_u32 s34, s34, 0x40000
	s_addc_u32 s35, s35, 0
	s_mov_b32 m0, s46
	v_lshl_add_u64 v[220:221], s[34:35], 0, v[0:1]
	ds_read_b128 v[164:167], v253 offset:32768
	ds_read_b128 v[168:171], v253 offset:33792
	ds_read_b128 v[172:175], v253 offset:34816
	ds_read_b128 v[176:179], v253 offset:35840
	ds_read_b128 v[180:183], v253 offset:36864
	ds_read_b128 v[184:187], v253 offset:37888
	ds_read_b128 v[188:191], v253 offset:38912
	ds_read_b128 v[192:195], v253 offset:39936
	global_load_lds_dwordx4 v[220:221], off
	s_mov_b32 m0, s47
	v_lshl_add_u64 v[220:221], s[34:35], 0, v[204:205]
	global_load_lds_dwordx4 v[220:221], off
	s_waitcnt vmcnt(8) lgkmcnt(0)
	s_barrier
	s_setprio 1
	v_mfma_f32_16x16x32_bf16 v[160:163], v[108:111], v[164:167], v[160:163]
	v_mfma_f32_16x16x32_bf16 v[152:155], v[124:127], v[164:167], v[152:155]
	v_mfma_f32_16x16x32_bf16 v[120:123], v[108:111], v[172:175], v[120:123]
	v_mfma_f32_16x16x32_bf16 v[116:119], v[124:127], v[172:175], v[116:119]
	v_mfma_f32_16x16x32_bf16 v[96:99], v[108:111], v[180:183], v[96:99]
	v_mfma_f32_16x16x32_bf16 v[92:95], v[124:127], v[180:183], v[92:95]
	v_mfma_f32_16x16x32_bf16 v[80:83], v[108:111], v[188:191], v[80:83]
	v_mfma_f32_16x16x32_bf16 v[76:79], v[124:127], v[188:191], v[76:79]
	s_setprio 0
	s_setprio 1
	v_mfma_f32_16x16x32_bf16 v[160:163], v[112:115], v[168:171], v[160:163]
	v_mfma_f32_16x16x32_bf16 v[152:155], v[128:131], v[168:171], v[152:155]
	v_mfma_f32_16x16x32_bf16 v[120:123], v[112:115], v[176:179], v[120:123]
	v_mfma_f32_16x16x32_bf16 v[116:119], v[128:131], v[176:179], v[116:119]
	v_mfma_f32_16x16x32_bf16 v[96:99], v[112:115], v[184:187], v[96:99]
	v_mfma_f32_16x16x32_bf16 v[92:95], v[128:131], v[184:187], v[92:95]
	v_mfma_f32_16x16x32_bf16 v[80:83], v[112:115], v[192:195], v[80:83]
	v_mfma_f32_16x16x32_bf16 v[76:79], v[128:131], v[192:195], v[76:79]
	s_setprio 0
	s_setprio 1
	v_mfma_f32_16x16x32_bf16 v[144:147], v[132:135], v[164:167], v[144:147]
	v_mfma_f32_16x16x32_bf16 v[136:139], v[148:151], v[164:167], v[136:139]
	v_mfma_f32_16x16x32_bf16 v[104:107], v[132:135], v[172:175], v[104:107]
	v_mfma_f32_16x16x32_bf16 v[100:103], v[148:151], v[172:175], v[100:103]
	v_mfma_f32_16x16x32_bf16 v[88:91], v[132:135], v[180:183], v[88:91]
	v_mfma_f32_16x16x32_bf16 v[84:87], v[148:151], v[180:183], v[84:87]
	v_mfma_f32_16x16x32_bf16 v[72:75], v[132:135], v[188:191], v[72:75]
	v_mfma_f32_16x16x32_bf16 v[68:71], v[148:151], v[188:191], v[68:71]
	s_setprio 0
	s_setprio 1
	v_mfma_f32_16x16x32_bf16 v[144:147], v[140:143], v[168:171], v[144:147]
	v_mfma_f32_16x16x32_bf16 v[136:139], v[156:159], v[168:171], v[136:139]
	v_mfma_f32_16x16x32_bf16 v[104:107], v[140:143], v[176:179], v[104:107]
	v_mfma_f32_16x16x32_bf16 v[100:103], v[156:159], v[176:179], v[100:103]
	v_mfma_f32_16x16x32_bf16 v[88:91], v[140:143], v[184:187], v[88:91]
	v_mfma_f32_16x16x32_bf16 v[84:87], v[156:159], v[184:187], v[84:87]
	v_mfma_f32_16x16x32_bf16 v[72:75], v[140:143], v[192:195], v[72:75]
	v_mfma_f32_16x16x32_bf16 v[68:71], v[156:159], v[192:195], v[68:71]
	s_setprio 0
	s_barrier
; #define PG8_STAGE(bufoff, gbase, voff) do { _Pragma("unroll") for (int _i = 0; _i < 2; ++_i) \
;         __builtin_amdgcn_global_load_lds((const unsigned*)((const char*)(gbase) + (voff)[_i]), (PG8_LAS unsigned*)(lds + (bufoff) + ldsw + _i * 8192), 16, 0, 0); } while (0)
; #define PG8_LDA(dst, b, h) do { _Pragma("unroll") for (int m = 0; m < 4; ++m) _Pragma("unroll") for (int k = 0; k < 2; ++k) dst[m][k] = *(const PG8_LAS bf16x8*)(lds + PG8_SA(b, h) + aoff + m * 2048 + k * 1024); } while (0)
; #define PG8_MMA(ai, bj, At, Bt) do { __builtin_amdgcn_s_setprio(1); _Pragma("unroll") for (int m = 0; m < 4; ++m) _Pragma("unroll") for (int n = 0; n < 2; ++n) _Pragma("unroll") for (int k = 0; k < 2; ++k) \
;         acc[ai][bj][m][n] = __builtin_amdgcn_mfma_f32_16x16x32_bf16(Bt[n][k], At[m][k], acc[ai][bj][m][n], 0, 0, 0); __builtin_amdgcn_s_setprio(0); } while (0)
; #define PG8_WAIT_V(n) asm volatile("s_waitcnt vmcnt(" #n ")" ::: "memory")
; #define PG8_WAIT_L(n) asm volatile("s_waitcnt lgkmcnt(" #n ")" ::: "memory")
; #define PG8_BAR __builtin_amdgcn_s_barrier()
; #define PG8_SCHED __builtin_amdgcn_sched_barrier(0)
; template <class Epi, class Sched, bool ALIGN_EPI = false, bool SP2 = false>
; __device__ __forceinline__ void gemm_phase(PG8_LAS unsigned char* lds, const Gemm g, const Sched& S, const Epi& E) {
;     ...
;             PG8_LDA(At, 1, 1); PG8_STAGE(PG8_SB(1, 0), b3, voffB); PG8_STAGE(PG8_SB(1, 1), b3 + hstep, voffB); PG8_STAGE(PG8_SA(1, 0), a3, voffA);
;             PG8_WAIT_V(8); PG8_WAIT_L(0); PG8_BAR; PG8_MMA(1, 0, At, B0); PG8_MMA(1, 1, At, B1); PG8_BAR; PG8_SCHED;
;     ...
;         if constexpr (ALIGN_EPI) { if (wr == 0) PG8_BAR; }
	s_add_i32 s34, s52, s41
	v_lshl_add_u64 v[212:213], v[212:213], 0, s[82:83]
	s_mov_b32 m0, s34
	ds_read_b128 v[164:167], v253 offset:49152
	ds_read_b128 v[168:171], v253 offset:50176
	ds_read_b128 v[172:175], v253 offset:51200
	ds_read_b128 v[176:179], v253 offset:52224
	ds_read_b128 v[180:183], v253 offset:53248
	ds_read_b128 v[184:187], v253 offset:54272
	ds_read_b128 v[188:191], v253 offset:55296
	ds_read_b128 v[192:195], v253 offset:56320
	global_load_lds_dwordx4 v[212:213], off
	s_add_i32 m0, s34, 0x2000
	s_add_u32 s30, s30, 0x40080
	v_lshl_add_u64 v[212:213], v[214:215], 0, s[82:83]
	s_addc_u32 s31, s31, 0
	s_add_i32 s34, s53, s41
	global_load_lds_dwordx4 v[212:213], off
	s_mov_b32 m0, s34
	v_lshl_add_u64 v[212:213], s[30:31], 0, v[202:203]
	global_load_lds_dwordx4 v[212:213], off
	s_add_i32 m0, s34, 0x2000
	v_lshl_add_u64 v[212:213], s[30:31], 0, v[206:207]
	global_load_lds_dwordx4 v[212:213], off
	s_mov_b32 m0, s49
	v_lshl_add_u64 v[212:213], v[216:217], 0, s[82:83]
	global_load_lds_dwordx4 v[212:213], off
	s_mov_b32 m0, s50
	v_lshl_add_u64 v[212:213], v[218:219], 0, s[82:83]
	global_load_lds_dwordx4 v[212:213], off
	s_waitcnt vmcnt(8) lgkmcnt(0)
	s_barrier
	s_setprio 1
	v_mfma_f32_16x16x32_bf16 v[64:67], v[108:111], v[164:167], v[64:67]
	v_mfma_f32_16x16x32_bf16 v[60:63], v[124:127], v[164:167], v[60:63]
	v_mfma_f32_16x16x32_bf16 v[48:51], v[108:111], v[172:175], v[48:51]
	v_mfma_f32_16x16x32_bf16 v[44:47], v[124:127], v[172:175], v[44:47]
	v_mfma_f32_16x16x32_bf16 v[32:35], v[108:111], v[180:183], v[32:35]
	v_mfma_f32_16x16x32_bf16 v[28:31], v[124:127], v[180:183], v[28:31]
	v_mfma_f32_16x16x32_bf16 v[16:19], v[108:111], v[188:191], v[16:19]
	v_mfma_f32_16x16x32_bf16 v[12:15], v[124:127], v[188:191], v[12:15]
	s_setprio 0
	s_setprio 1
	v_mfma_f32_16x16x32_bf16 v[64:67], v[112:115], v[168:171], v[64:67]
	v_mfma_f32_16x16x32_bf16 v[60:63], v[128:131], v[168:171], v[60:63]
	v_mfma_f32_16x16x32_bf16 v[48:51], v[112:115], v[176:179], v[48:51]
	v_mfma_f32_16x16x32_bf16 v[44:47], v[128:131], v[176:179], v[44:47]
	v_mfma_f32_16x16x32_bf16 v[32:35], v[112:115], v[184:187], v[32:35]
	v_mfma_f32_16x16x32_bf16 v[28:31], v[128:131], v[184:187], v[28:31]
	v_mfma_f32_16x16x32_bf16 v[16:19], v[112:115], v[192:195], v[16:19]
	v_mfma_f32_16x16x32_bf16 v[12:15], v[128:131], v[192:195], v[12:15]
	s_setprio 0
	s_setprio 1
	v_mfma_f32_16x16x32_bf16 v[56:59], v[132:135], v[164:167], v[56:59]
	v_mfma_f32_16x16x32_bf16 v[52:55], v[148:151], v[164:167], v[52:55]
	v_mfma_f32_16x16x32_bf16 v[40:43], v[132:135], v[172:175], v[40:43]
	v_mfma_f32_16x16x32_bf16 v[36:39], v[148:151], v[172:175], v[36:39]
	v_mfma_f32_16x16x32_bf16 v[24:27], v[132:135], v[180:183], v[24:27]
	v_mfma_f32_16x16x32_bf16 v[20:23], v[148:151], v[180:183], v[20:23]
	v_mfma_f32_16x16x32_bf16 v[8:11], v[132:135], v[188:191], v[8:11]
	v_mfma_f32_16x16x32_bf16 v[4:7], v[148:151], v[188:191], v[4:7]
	s_setprio 0
	s_setprio 1
	v_mfma_f32_16x16x32_bf16 v[56:59], v[140:143], v[168:171], v[56:59]
	v_mfma_f32_16x16x32_bf16 v[52:55], v[156:159], v[168:171], v[52:55]
	v_mfma_f32_16x16x32_bf16 v[40:43], v[140:143], v[176:179], v[40:43]
	v_mfma_f32_16x16x32_bf16 v[36:39], v[156:159], v[176:179], v[36:39]
	v_mfma_f32_16x16x32_bf16 v[24:27], v[140:143], v[184:187], v[24:27]
	v_mfma_f32_16x16x32_bf16 v[20:23], v[156:159], v[184:187], v[20:23]
	v_mfma_f32_16x16x32_bf16 v[8:11], v[140:143], v[192:195], v[8:11]
	v_mfma_f32_16x16x32_bf16 v[4:7], v[156:159], v[192:195], v[4:7]
	s_setprio 0
	s_barrier
	s_add_i32 s45, s45, 2
	s_add_u32 s28, s28, 0x100
	s_addc_u32 s29, s29, 0
	s_add_u32 s27, s27, 0x100
	s_addc_u32 s44, s44, 0
	s_cmp_gt_u32 s45, 13
	s_cbranch_scc0 .LBB0_329
	s_and_b64 vcc, exec, s[14:15]
	s_cbranch_vccz .LBB0_332
	s_barrier

; #define PG8_STAGE(bufoff, gbase, voff) do { _Pragma("unroll") for (int _i = 0; _i < 2; ++_i) \
;         __builtin_amdgcn_global_load_lds((const unsigned*)((const char*)(gbase) + (voff)[_i]), (PG8_LAS unsigned*)(lds + (bufoff) + ldsw + _i * 8192), 16, 0, 0); } while (0)
; #define PG8_LDA(dst, b, h) do { _Pragma("unroll") for (int m = 0; m < 4; ++m) _Pragma("unroll") for (int k = 0; k < 2; ++k) dst[m][k] = *(const PG8_LAS bf16x8*)(lds + PG8_SA(b, h) + aoff + m * 2048 + k * 1024); } while (0)
; #define PG8_LDB(dst, b, h) do { _Pragma("unroll") for (int n = 0; n < 2; ++n) _Pragma("unroll") for (int k = 0; k < 2; ++k) dst[n][k] = *(const PG8_LAS bf16x8*)(lds + PG8_SB(b, h) + boff + n * 2048 + k * 1024); } while (0)
; #define PG8_MMA(ai, bj, At, Bt) do { __builtin_amdgcn_s_setprio(1); _Pragma("unroll") for (int m = 0; m < 4; ++m) _Pragma("unroll") for (int n = 0; n < 2; ++n) _Pragma("unroll") for (int k = 0; k < 2; ++k) \
;         acc[ai][bj][m][n] = __builtin_amdgcn_mfma_f32_16x16x32_bf16(Bt[n][k], At[m][k], acc[ai][bj][m][n], 0, 0, 0); __builtin_amdgcn_s_setprio(0); } while (0)
; #define PG8_WAIT_V(n) asm volatile("s_waitcnt vmcnt(" #n ")" ::: "memory")
; #define PG8_BAR __builtin_amdgcn_s_barrier()
; template <class Epi, class Sched, bool ALIGN_EPI = false, bool SP2 = false>
; __device__ __forceinline__ void gemm_phase(PG8_LAS unsigned char* lds, const Gemm g, const Sched& S, const Epi& E) {
;     ...
;         for (int t = 0; t < nt; t += 2) {
;             const bool last = (t == nt - 2);
;             const char* a1 = cA + (size_t)(t + 1) * kstep;
;             const char* a2 = last ? nA : cA + (size_t)(t + 2) * kstep; const char* b2 = last ? nB : cB + (size_t)(t + 2) * kstep;
;             const char* a3 = a2 + kstep; const char* b3 = b2 + kstep;
;             if (last && has_next) S.a_ready(nxt);
;             if constexpr (SP2) {
;             PG8_LDB(B0, 0, 0); PG8_LDB(B1, 0, 1); PG8_SCHED; PG8_LDA(At, 0, 0); PG8_STAGE(PG8_SA(1, 1), a1 + hstep, voffA);
;             PG8_WAIT_V(8); PG8_WAIT_L(0); PG8_BAR; PG8_MMA(0, 0, At, B0); PG8_MMA(0, 1, At, B1); PG8_BAR; PG8_SCHED;
;             PG8_LDA(At, 0, 1); PG8_STAGE(PG8_SB(0, 0), b2, voffB); PG8_STAGE(PG8_SB(0, 1), b2 + hstep, voffB); PG8_STAGE(PG8_SA(0, 0), a2, voffA);
;             PG8_WAIT_V(8); PG8_WAIT_L(0); PG8_BAR; PG8_MMA(1, 0, At, B0); PG8_MMA(1, 1, At, B1); PG8_BAR; PG8_SCHED;
.LBB0_405:
	s_add_u32 s24, s8, 0xfffc0080
	s_addc_u32 s25, s9, -1
	s_add_i32 s47, 0, 0x10000
	s_cmp_eq_u32 s46, 12
	s_cselect_b32 s27, s7, s25
	s_cselect_b32 s26, s17, s24
	s_cselect_b32 s25, s19, s45
	s_cselect_b32 s24, s43, s44
	s_add_i32 s50, 0, 0x14000
	v_add_u32_e32 v156, s47, v164
	v_add_u32_e32 v167, s50, v164
	ds_read_b128 v[144:147], v156
	ds_read_b128 v[148:151], v156 offset:1024
	ds_read_b128 v[152:155], v156 offset:2048
	ds_read_b128 v[156:159], v156 offset:3072
	ds_read_b128 v[160:163], v167
	ds_read_b128 v[168:171], v167 offset:1024
	ds_read_b128 v[172:175], v167 offset:2048
	ds_read_b128 v[176:179], v167 offset:3072
	v_lshl_add_u64 v[198:199], s[8:9], 0, v[140:141]
	s_add_i32 m0, s37, 0xc000
	ds_read_b128 v[180:183], v166
	ds_read_b128 v[184:187], v166 offset:1024
	ds_read_b128 v[188:191], v166 offset:2048
	ds_read_b128 v[192:195], v166 offset:3072
	ds_read_b128 v[202:205], v166 offset:4096
	ds_read_b128 v[206:209], v166 offset:5120
	ds_read_b128 v[210:213], v166 offset:6144
	ds_read_b128 v[214:217], v166 offset:7168
	global_load_lds_dwordx4 v[198:199], off
	s_add_i32 m0, s37, 0xe000
	v_lshl_add_u64 v[198:199], s[8:9], 0, v[142:143]
	global_load_lds_dwordx4 v[198:199], off
	s_waitcnt vmcnt(8) lgkmcnt(0)
	s_barrier
	s_setprio 1
	v_mfma_f32_16x16x32_bf16 v[128:131], v[144:147], v[180:183], v[128:131]
	v_mfma_f32_16x16x32_bf16 v[120:123], v[152:155], v[180:183], v[120:123]
	v_mfma_f32_16x16x32_bf16 v[112:115], v[144:147], v[188:191], v[112:115]
	v_mfma_f32_16x16x32_bf16 v[104:107], v[152:155], v[188:191], v[104:107]
	v_mfma_f32_16x16x32_bf16 v[96:99], v[144:147], v[202:205], v[96:99]
	v_mfma_f32_16x16x32_bf16 v[88:91], v[152:155], v[202:205], v[88:91]
	v_mfma_f32_16x16x32_bf16 v[80:83], v[144:147], v[210:213], v[80:83]
	v_mfma_f32_16x16x32_bf16 v[72:75], v[152:155], v[210:213], v[72:75]
	s_setprio 0
	s_setprio 1
	v_mfma_f32_16x16x32_bf16 v[128:131], v[148:151], v[184:187], v[128:131]
	v_mfma_f32_16x16x32_bf16 v[120:123], v[156:159], v[184:187], v[120:123]
	v_mfma_f32_16x16x32_bf16 v[112:115], v[148:151], v[192:195], v[112:115]
	v_mfma_f32_16x16x32_bf16 v[104:107], v[156:159], v[192:195], v[104:107]
	v_mfma_f32_16x16x32_bf16 v[96:99], v[148:151], v[206:209], v[96:99]
	v_mfma_f32_16x16x32_bf16 v[88:91], v[156:159], v[206:209], v[88:91]
	v_mfma_f32_16x16x32_bf16 v[80:83], v[148:151], v[214:217], v[80:83]
	v_mfma_f32_16x16x32_bf16 v[72:75], v[156:159], v[214:217], v[72:75]
	s_setprio 0
	s_setprio 1
	v_mfma_f32_16x16x32_bf16 v[124:127], v[160:163], v[180:183], v[124:127]
	v_mfma_f32_16x16x32_bf16 v[116:119], v[172:175], v[180:183], v[116:119]
	v_mfma_f32_16x16x32_bf16 v[108:111], v[160:163], v[188:191], v[108:111]
	v_mfma_f32_16x16x32_bf16 v[100:103], v[172:175], v[188:191], v[100:103]
	v_mfma_f32_16x16x32_bf16 v[92:95], v[160:163], v[202:205], v[92:95]
	v_mfma_f32_16x16x32_bf16 v[84:87], v[172:175], v[202:205], v[84:87]
	v_mfma_f32_16x16x32_bf16 v[76:79], v[160:163], v[210:213], v[76:79]
	v_mfma_f32_16x16x32_bf16 v[68:71], v[172:175], v[210:213], v[68:71]
	s_setprio 0
	s_setprio 1
	v_mfma_f32_16x16x32_bf16 v[124:127], v[168:171], v[184:187], v[124:127]
	v_mfma_f32_16x16x32_bf16 v[116:119], v[176:179], v[184:187], v[116:119]
	v_mfma_f32_16x16x32_bf16 v[108:111], v[168:171], v[192:195], v[108:111]
	v_mfma_f32_16x16x32_bf16 v[100:103], v[176:179], v[192:195], v[100:103]
	v_mfma_f32_16x16x32_bf16 v[92:95], v[168:171], v[206:209], v[92:95]
	v_mfma_f32_16x16x32_bf16 v[84:87], v[176:179], v[206:209], v[84:87]
	v_mfma_f32_16x16x32_bf16 v[76:79], v[168:171], v[214:217], v[76:79]
	v_mfma_f32_16x16x32_bf16 v[68:71], v[176:179], v[214:217], v[68:71]
	s_setprio 0
	s_barrier
	s_add_i32 s47, s47, s35
	v_lshl_add_u64 v[198:199], s[24:25], 0, v[134:135]
	s_mov_b32 m0, s47
	ds_read_b128 v[180:183], v166 offset:16384
	ds_read_b128 v[184:187], v166 offset:17408
	ds_read_b128 v[188:191], v166 offset:18432
	ds_read_b128 v[192:195], v166 offset:19456
	ds_read_b128 v[202:205], v166 offset:20480
	ds_read_b128 v[206:209], v166 offset:21504
	ds_read_b128 v[210:213], v166 offset:22528
	ds_read_b128 v[214:217], v166 offset:23552
	global_load_lds_dwordx4 v[198:199], off
	s_add_i32 m0, s47, 0x2000
	s_add_u32 s48, s24, 0x40000
	v_lshl_add_u64 v[218:219], s[24:25], 0, v[0:1]
	s_addc_u32 s49, s25, 0
	s_add_i32 s47, s50, s35
	global_load_lds_dwordx4 v[218:219], off
	v_lshl_add_u64 v[220:221], s[48:49], 0, v[134:135]
	s_mov_b32 m0, s47
	v_lshl_add_u64 v[222:223], s[26:27], 0, v[132:133]
	global_load_lds_dwordx4 v[220:221], off
	s_add_i32 m0, s47, 0x2000
	v_lshl_add_u64 v[220:221], s[48:49], 0, v[0:1]
	global_load_lds_dwordx4 v[220:221], off
	s_mov_b32 m0, s37
	v_lshl_add_u64 v[220:221], s[26:27], 0, v[136:137]
	global_load_lds_dwordx4 v[220:221], off
	s_mov_b32 m0, s38
	s_add_i32 s47, 0, 0x18000
	global_load_lds_dwordx4 v[222:223], off
	s_waitcnt vmcnt(8) lgkmcnt(0)
	s_barrier
; #define PG8_STAGE(bufoff, gbase, voff) do { _Pragma("unroll") for (int _i = 0; _i < 2; ++_i) \
;         __builtin_amdgcn_global_load_lds((const unsigned*)((const char*)(gbase) + (voff)[_i]), (PG8_LAS unsigned*)(lds + (bufoff) + ldsw + _i * 8192), 16, 0, 0); } while (0)
; #define PG8_LDA(dst, b, h) do { _Pragma("unroll") for (int m = 0; m < 4; ++m) _Pragma("unroll") for (int k = 0; k < 2; ++k) dst[m][k] = *(const PG8_LAS bf16x8*)(lds + PG8_SA(b, h) + aoff + m * 2048 + k * 1024); } while (0)
; #define PG8_LDB(dst, b, h) do { _Pragma("unroll") for (int n = 0; n < 2; ++n) _Pragma("unroll") for (int k = 0; k < 2; ++k) dst[n][k] = *(const PG8_LAS bf16x8*)(lds + PG8_SB(b, h) + boff + n * 2048 + k * 1024); } while (0)
; #define PG8_MMA(ai, bj, At, Bt) do { __builtin_amdgcn_s_setprio(1); _Pragma("unroll") for (int m = 0; m < 4; ++m) _Pragma("unroll") for (int n = 0; n < 2; ++n) _Pragma("unroll") for (int k = 0; k < 2; ++k) \
;         acc[ai][bj][m][n] = __builtin_amdgcn_mfma_f32_16x16x32_bf16(Bt[n][k], At[m][k], acc[ai][bj][m][n], 0, 0, 0); __builtin_amdgcn_s_setprio(0); } while (0)
; #define PG8_WAIT_V(n) asm volatile("s_waitcnt vmcnt(" #n ")" ::: "memory")
; #define PG8_WAIT_L(n) asm volatile("s_waitcnt lgkmcnt(" #n ")" ::: "memory")
; #define PG8_BAR __builtin_amdgcn_s_barrier()
; #define PG8_SCHED __builtin_amdgcn_sched_barrier(0)
; template <class Epi, class Sched, bool ALIGN_EPI = false, bool SP2 = false>
; __device__ __forceinline__ void gemm_phase(PG8_LAS unsigned char* lds, const Gemm g, const Sched& S, const Epi& E) {
;     ...
;             PG8_WAIT_V(8); PG8_WAIT_L(0); PG8_BAR; PG8_MMA(1, 0, At, B0); PG8_MMA(1, 1, At, B1); PG8_BAR; PG8_SCHED;
;             PG8_LDB(B0, 1, 0); PG8_LDB(B1, 1, 1); PG8_SCHED; PG8_LDA(At, 1, 0); PG8_STAGE(PG8_SA(0, 1), a2 + hstep, voffA);
;             PG8_WAIT_V(8); PG8_WAIT_L(0); PG8_BAR; PG8_MMA(0, 0, At, B0); PG8_MMA(0, 1, At, B1); PG8_BAR; PG8_SCHED;
	s_setprio 1
	v_mfma_f32_16x16x32_bf16 v[64:67], v[144:147], v[180:183], v[64:67]
	v_mfma_f32_16x16x32_bf16 v[56:59], v[152:155], v[180:183], v[56:59]
	v_mfma_f32_16x16x32_bf16 v[48:51], v[144:147], v[188:191], v[48:51]
	v_mfma_f32_16x16x32_bf16 v[40:43], v[152:155], v[188:191], v[40:43]
	v_mfma_f32_16x16x32_bf16 v[32:35], v[144:147], v[202:205], v[32:35]
	v_mfma_f32_16x16x32_bf16 v[24:27], v[152:155], v[202:205], v[24:27]
	v_mfma_f32_16x16x32_bf16 v[16:19], v[144:147], v[210:213], v[16:19]
	v_mfma_f32_16x16x32_bf16 v[8:11], v[152:155], v[210:213], v[8:11]
	s_setprio 0
	s_setprio 1
	v_mfma_f32_16x16x32_bf16 v[64:67], v[148:151], v[184:187], v[64:67]
	v_mfma_f32_16x16x32_bf16 v[56:59], v[156:159], v[184:187], v[56:59]
	v_mfma_f32_16x16x32_bf16 v[48:51], v[148:151], v[192:195], v[48:51]
	v_mfma_f32_16x16x32_bf16 v[40:43], v[156:159], v[192:195], v[40:43]
	v_mfma_f32_16x16x32_bf16 v[32:35], v[148:151], v[206:209], v[32:35]
	v_mfma_f32_16x16x32_bf16 v[24:27], v[156:159], v[206:209], v[24:27]
	v_mfma_f32_16x16x32_bf16 v[16:19], v[148:151], v[214:217], v[16:19]
	v_mfma_f32_16x16x32_bf16 v[8:11], v[156:159], v[214:217], v[8:11]
	s_setprio 0
	s_setprio 1
	v_mfma_f32_16x16x32_bf16 v[60:63], v[160:163], v[180:183], v[60:63]
	v_mfma_f32_16x16x32_bf16 v[52:55], v[172:175], v[180:183], v[52:55]
	v_mfma_f32_16x16x32_bf16 v[44:47], v[160:163], v[188:191], v[44:47]
	v_mfma_f32_16x16x32_bf16 v[36:39], v[172:175], v[188:191], v[36:39]
	v_mfma_f32_16x16x32_bf16 v[28:31], v[160:163], v[202:205], v[28:31]
	v_mfma_f32_16x16x32_bf16 v[20:23], v[172:175], v[202:205], v[20:23]
	v_mfma_f32_16x16x32_bf16 v[12:15], v[160:163], v[210:213], v[12:15]
	v_mfma_f32_16x16x32_bf16 v[4:7], v[172:175], v[210:213], v[4:7]
	s_setprio 0
	s_setprio 1
	v_mfma_f32_16x16x32_bf16 v[60:63], v[168:171], v[184:187], v[60:63]
	v_mfma_f32_16x16x32_bf16 v[52:55], v[176:179], v[184:187], v[52:55]
	v_mfma_f32_16x16x32_bf16 v[44:47], v[168:171], v[192:195], v[44:47]
	v_mfma_f32_16x16x32_bf16 v[36:39], v[176:179], v[192:195], v[36:39]
	v_mfma_f32_16x16x32_bf16 v[28:31], v[168:171], v[206:209], v[28:31]
	v_mfma_f32_16x16x32_bf16 v[20:23], v[176:179], v[206:209], v[20:23]
	v_mfma_f32_16x16x32_bf16 v[12:15], v[168:171], v[214:217], v[12:15]
	v_mfma_f32_16x16x32_bf16 v[4:7], v[176:179], v[214:217], v[4:7]
	s_setprio 0
	s_barrier
	s_add_i32 s48, 0, 0x1c000
	v_add_u32_e32 v156, s47, v164
	v_add_u32_e32 v167, s48, v164
	ds_read_b128 v[144:147], v156
	ds_read_b128 v[148:151], v156 offset:1024
	ds_read_b128 v[152:155], v156 offset:2048
	ds_read_b128 v[156:159], v156 offset:3072
	ds_read_b128 v[160:163], v167
	ds_read_b128 v[168:171], v167 offset:1024
	ds_read_b128 v[172:175], v167 offset:2048
	ds_read_b128 v[176:179], v167 offset:3072
	s_add_u32 s26, s26, 0x40000
	s_addc_u32 s27, s27, 0
	s_mov_b32 m0, s39
	v_lshl_add_u64 v[224:225], s[26:27], 0, v[136:137]
	ds_read_b128 v[180:183], v166 offset:32768
	ds_read_b128 v[184:187], v166 offset:33792
	ds_read_b128 v[188:191], v166 offset:34816
	ds_read_b128 v[192:195], v166 offset:35840
	ds_read_b128 v[202:205], v166 offset:36864
	ds_read_b128 v[206:209], v166 offset:37888
	ds_read_b128 v[210:213], v166 offset:38912
	ds_read_b128 v[214:217], v166 offset:39936
	global_load_lds_dwordx4 v[224:225], off
	s_mov_b32 m0, s40
	v_lshl_add_u64 v[224:225], s[26:27], 0, v[132:133]
	global_load_lds_dwordx4 v[224:225], off
	s_waitcnt vmcnt(8) lgkmcnt(0)
	s_barrier
	s_setprio 1
	v_mfma_f32_16x16x32_bf16 v[128:131], v[144:147], v[180:183], v[128:131]
	v_mfma_f32_16x16x32_bf16 v[120:123], v[152:155], v[180:183], v[120:123]
	v_mfma_f32_16x16x32_bf16 v[112:115], v[144:147], v[188:191], v[112:115]
	v_mfma_f32_16x16x32_bf16 v[104:107], v[152:155], v[188:191], v[104:107]
	v_mfma_f32_16x16x32_bf16 v[96:99], v[144:147], v[202:205], v[96:99]
	v_mfma_f32_16x16x32_bf16 v[88:91], v[152:155], v[202:205], v[88:91]
	v_mfma_f32_16x16x32_bf16 v[80:83], v[144:147], v[210:213], v[80:83]
	v_mfma_f32_16x16x32_bf16 v[72:75], v[152:155], v[210:213], v[72:75]
	s_setprio 0
	s_setprio 1
	v_mfma_f32_16x16x32_bf16 v[128:131], v[148:151], v[184:187], v[128:131]
	v_mfma_f32_16x16x32_bf16 v[120:123], v[156:159], v[184:187], v[120:123]
	v_mfma_f32_16x16x32_bf16 v[112:115], v[148:151], v[192:195], v[112:115]
	v_mfma_f32_16x16x32_bf16 v[104:107], v[156:159], v[192:195], v[104:107]
	v_mfma_f32_16x16x32_bf16 v[96:99], v[148:151], v[206:209], v[96:99]
	v_mfma_f32_16x16x32_bf16 v[88:91], v[156:159], v[206:209], v[88:91]
	v_mfma_f32_16x16x32_bf16 v[80:83], v[148:151], v[214:217], v[80:83]
	v_mfma_f32_16x16x32_bf16 v[72:75], v[156:159], v[214:217], v[72:75]
	s_setprio 0
	s_setprio 1
	v_mfma_f32_16x16x32_bf16 v[124:127], v[160:163], v[180:183], v[124:127]
	v_mfma_f32_16x16x32_bf16 v[116:119], v[172:175], v[180:183], v[116:119]
	v_mfma_f32_16x16x32_bf16 v[108:111], v[160:163], v[188:191], v[108:111]
	v_mfma_f32_16x16x32_bf16 v[100:103], v[172:175], v[188:191], v[100:103]
	v_mfma_f32_16x16x32_bf16 v[92:95], v[160:163], v[202:205], v[92:95]
	v_mfma_f32_16x16x32_bf16 v[84:87], v[172:175], v[202:205], v[84:87]
	v_mfma_f32_16x16x32_bf16 v[76:79], v[160:163], v[210:213], v[76:79]
	v_mfma_f32_16x16x32_bf16 v[68:71], v[172:175], v[210:213], v[68:71]
	s_setprio 0
	s_setprio 1
	v_mfma_f32_16x16x32_bf16 v[124:127], v[168:171], v[184:187], v[124:127]
	v_mfma_f32_16x16x32_bf16 v[116:119], v[176:179], v[184:187], v[116:119]
	v_mfma_f32_16x16x32_bf16 v[108:111], v[168:171], v[192:195], v[108:111]
	v_mfma_f32_16x16x32_bf16 v[100:103], v[176:179], v[192:195], v[100:103]
	v_mfma_f32_16x16x32_bf16 v[92:95], v[168:171], v[206:209], v[92:95]
	v_mfma_f32_16x16x32_bf16 v[84:87], v[176:179], v[206:209], v[84:87]
	v_mfma_f32_16x16x32_bf16 v[76:79], v[168:171], v[214:217], v[76:79]
	v_mfma_f32_16x16x32_bf16 v[68:71], v[176:179], v[214:217], v[68:71]
	s_setprio 0
	s_barrier
; #define PG8_STAGE(bufoff, gbase, voff) do { _Pragma("unroll") for (int _i = 0; _i < 2; ++_i) \
;         __builtin_amdgcn_global_load_lds((const unsigned*)((const char*)(gbase) + (voff)[_i]), (PG8_LAS unsigned*)(lds + (bufoff) + ldsw + _i * 8192), 16, 0, 0); } while (0)
; #define PG8_LDA(dst, b, h) do { _Pragma("unroll") for (int m = 0; m < 4; ++m) _Pragma("unroll") for (int k = 0; k < 2; ++k) dst[m][k] = *(const PG8_LAS bf16x8*)(lds + PG8_SA(b, h) + aoff + m * 2048 + k * 1024); } while (0)
; #define PG8_MMA(ai, bj, At, Bt) do { __builtin_amdgcn_s_setprio(1); _Pragma("unroll") for (int m = 0; m < 4; ++m) _Pragma("unroll") for (int n = 0; n < 2; ++n) _Pragma("unroll") for (int k = 0; k < 2; ++k) \
;         acc[ai][bj][m][n] = __builtin_amdgcn_mfma_f32_16x16x32_bf16(Bt[n][k], At[m][k], acc[ai][bj][m][n], 0, 0, 0); __builtin_amdgcn_s_setprio(0); } while (0)
; #define PG8_WAIT_V(n) asm volatile("s_waitcnt vmcnt(" #n ")" ::: "memory")
; #define PG8_WAIT_L(n) asm volatile("s_waitcnt lgkmcnt(" #n ")" ::: "memory")
; #define PG8_BAR __builtin_amdgcn_s_barrier()
; #define PG8_SCHED __builtin_amdgcn_sched_barrier(0)
; template <class Epi, class Sched, bool ALIGN_EPI = false, bool SP2 = false>
; __device__ __forceinline__ void gemm_phase(PG8_LAS unsigned char* lds, const Gemm g, const Sched& S, const Epi& E) {
;     ...
;             PG8_LDA(At, 1, 1); PG8_STAGE(PG8_SB(1, 0), b3, voffB); PG8_STAGE(PG8_SB(1, 1), b3 + hstep, voffB); PG8_STAGE(PG8_SA(1, 0), a3, voffA);
;             PG8_WAIT_V(8); PG8_WAIT_L(0); PG8_BAR; PG8_MMA(1, 0, At, B0); PG8_MMA(1, 1, At, B1); PG8_BAR; PG8_SCHED;
;     ...
;         if constexpr (ALIGN_EPI) { if (wr == 0) PG8_BAR; }
	s_add_i32 s26, s47, s35
	v_lshl_add_u64 v[198:199], v[198:199], 0, s[82:83]
	s_mov_b32 m0, s26
	ds_read_b128 v[180:183], v166 offset:49152
	ds_read_b128 v[184:187], v166 offset:50176
	ds_read_b128 v[188:191], v166 offset:51200
	ds_read_b128 v[192:195], v166 offset:52224
	ds_read_b128 v[202:205], v166 offset:53248
	ds_read_b128 v[206:209], v166 offset:54272
	ds_read_b128 v[210:213], v166 offset:55296
	ds_read_b128 v[214:217], v166 offset:56320
	global_load_lds_dwordx4 v[198:199], off
	s_add_i32 m0, s26, 0x2000
	s_add_u32 s24, s24, 0x40080
	v_lshl_add_u64 v[198:199], v[218:219], 0, s[82:83]
	s_addc_u32 s25, s25, 0
	s_add_i32 s26, s48, s35
	global_load_lds_dwordx4 v[198:199], off
	s_mov_b32 m0, s26
	v_lshl_add_u64 v[198:199], s[24:25], 0, v[134:135]
	global_load_lds_dwordx4 v[198:199], off
	s_add_i32 m0, s26, 0x2000
	v_lshl_add_u64 v[198:199], s[24:25], 0, v[0:1]
	global_load_lds_dwordx4 v[198:199], off
	s_mov_b32 m0, s41
	v_lshl_add_u64 v[198:199], v[220:221], 0, s[82:83]
	global_load_lds_dwordx4 v[198:199], off
	s_mov_b32 m0, s42
	v_lshl_add_u64 v[198:199], v[222:223], 0, s[82:83]
	global_load_lds_dwordx4 v[198:199], off
	s_waitcnt vmcnt(8) lgkmcnt(0)
	s_barrier
	s_setprio 1
	v_mfma_f32_16x16x32_bf16 v[64:67], v[144:147], v[180:183], v[64:67]
	v_mfma_f32_16x16x32_bf16 v[56:59], v[152:155], v[180:183], v[56:59]
	v_mfma_f32_16x16x32_bf16 v[48:51], v[144:147], v[188:191], v[48:51]
	v_mfma_f32_16x16x32_bf16 v[40:43], v[152:155], v[188:191], v[40:43]
	v_mfma_f32_16x16x32_bf16 v[32:35], v[144:147], v[202:205], v[32:35]
	v_mfma_f32_16x16x32_bf16 v[24:27], v[152:155], v[202:205], v[24:27]
	v_mfma_f32_16x16x32_bf16 v[16:19], v[144:147], v[210:213], v[16:19]
	v_mfma_f32_16x16x32_bf16 v[8:11], v[152:155], v[210:213], v[8:11]
	s_setprio 0
	s_setprio 1
	v_mfma_f32_16x16x32_bf16 v[64:67], v[148:151], v[184:187], v[64:67]
	v_mfma_f32_16x16x32_bf16 v[56:59], v[156:159], v[184:187], v[56:59]
	v_mfma_f32_16x16x32_bf16 v[48:51], v[148:151], v[192:195], v[48:51]
	v_mfma_f32_16x16x32_bf16 v[40:43], v[156:159], v[192:195], v[40:43]
	v_mfma_f32_16x16x32_bf16 v[32:35], v[148:151], v[206:209], v[32:35]
	v_mfma_f32_16x16x32_bf16 v[24:27], v[156:159], v[206:209], v[24:27]
	v_mfma_f32_16x16x32_bf16 v[16:19], v[148:151], v[214:217], v[16:19]
	v_mfma_f32_16x16x32_bf16 v[8:11], v[156:159], v[214:217], v[8:11]
	s_setprio 0
	s_setprio 1
	v_mfma_f32_16x16x32_bf16 v[60:63], v[160:163], v[180:183], v[60:63]
	v_mfma_f32_16x16x32_bf16 v[52:55], v[172:175], v[180:183], v[52:55]
	v_mfma_f32_16x16x32_bf16 v[44:47], v[160:163], v[188:191], v[44:47]
	v_mfma_f32_16x16x32_bf16 v[36:39], v[172:175], v[188:191], v[36:39]
	v_mfma_f32_16x16x32_bf16 v[28:31], v[160:163], v[202:205], v[28:31]
	v_mfma_f32_16x16x32_bf16 v[20:23], v[172:175], v[202:205], v[20:23]
	v_mfma_f32_16x16x32_bf16 v[12:15], v[160:163], v[210:213], v[12:15]
	v_mfma_f32_16x16x32_bf16 v[4:7], v[172:175], v[210:213], v[4:7]
	s_setprio 0
	s_setprio 1
	v_mfma_f32_16x16x32_bf16 v[60:63], v[168:171], v[184:187], v[60:63]
	v_mfma_f32_16x16x32_bf16 v[52:55], v[176:179], v[184:187], v[52:55]
	v_mfma_f32_16x16x32_bf16 v[44:47], v[168:171], v[192:195], v[44:47]
	v_mfma_f32_16x16x32_bf16 v[36:39], v[176:179], v[192:195], v[36:39]
	v_mfma_f32_16x16x32_bf16 v[28:31], v[168:171], v[206:209], v[28:31]
	v_mfma_f32_16x16x32_bf16 v[20:23], v[176:179], v[206:209], v[20:23]
	v_mfma_f32_16x16x32_bf16 v[12:15], v[168:171], v[214:217], v[12:15]
	v_mfma_f32_16x16x32_bf16 v[4:7], v[176:179], v[214:217], v[4:7]
	s_setprio 0
	s_barrier
	s_add_i32 s46, s46, 2
	s_add_u32 s8, s8, 0x100
	s_addc_u32 s9, s9, 0
	s_add_u32 s44, s44, 0x100
	s_addc_u32 s45, s45, 0
	s_cmp_gt_u32 s46, 13
	s_cbranch_scc0 .LBB0_405
	s_and_b64 vcc, exec, s[14:15]
	s_cbranch_vccz .LBB0_408
	s_barrier

; #define PG8_STAGE(bufoff, gbase, voff) do { _Pragma("unroll") for (int _i = 0; _i < 2; ++_i) \
;         __builtin_amdgcn_global_load_lds((const unsigned*)((const char*)(gbase) + (voff)[_i]), (PG8_LAS unsigned*)(lds + (bufoff) + ldsw + _i * 8192), 16, 0, 0); } while (0)
; #define PG8_LDA(dst, b, h) do { _Pragma("unroll") for (int m = 0; m < 4; ++m) _Pragma("unroll") for (int k = 0; k < 2; ++k) dst[m][k] = *(const PG8_LAS bf16x8*)(lds + PG8_SA(b, h) + aoff + m * 2048 + k * 1024); } while (0)
; #define PG8_LDB(dst, b, h) do { _Pragma("unroll") for (int n = 0; n < 2; ++n) _Pragma("unroll") for (int k = 0; k < 2; ++k) dst[n][k] = *(const PG8_LAS bf16x8*)(lds + PG8_SB(b, h) + boff + n * 2048 + k * 1024); } while (0)
; #define PG8_MMA(ai, bj, At, Bt) do { __builtin_amdgcn_s_setprio(1); _Pragma("unroll") for (int m = 0; m < 4; ++m) _Pragma("unroll") for (int n = 0; n < 2; ++n) _Pragma("unroll") for (int k = 0; k < 2; ++k) \
;         acc[ai][bj][m][n] = __builtin_amdgcn_mfma_f32_16x16x32_bf16(Bt[n][k], At[m][k], acc[ai][bj][m][n], 0, 0, 0); __builtin_amdgcn_s_setprio(0); } while (0)
; #define PG8_WAIT_V(n) asm volatile("s_waitcnt vmcnt(" #n ")" ::: "memory")
; #define PG8_BAR __builtin_amdgcn_s_barrier()
; template <class Epi, class Sched, bool ALIGN_EPI = false, bool SP2 = false>
; __device__ __forceinline__ void gemm_phase(PG8_LAS unsigned char* lds, const Gemm g, const Sched& S, const Epi& E) {
;     ...
;         for (int t = 0; t < nt; t += 2) {
;             const bool last = (t == nt - 2);
;             const char* a1 = cA + (size_t)(t + 1) * kstep;
;             const char* a2 = last ? nA : cA + (size_t)(t + 2) * kstep; const char* b2 = last ? nB : cB + (size_t)(t + 2) * kstep;
;             const char* a3 = a2 + kstep; const char* b3 = b2 + kstep;
;             if (last && has_next) S.a_ready(nxt);
;             if constexpr (SP2) {
;             PG8_LDB(B0, 0, 0); PG8_LDB(B1, 0, 1); PG8_SCHED; PG8_LDA(At, 0, 0); PG8_STAGE(PG8_SA(1, 1), a1 + hstep, voffA);
;             PG8_WAIT_V(8); PG8_WAIT_L(0); PG8_BAR; PG8_MMA(0, 0, At, B0); PG8_MMA(0, 1, At, B1); PG8_BAR; PG8_SCHED;
;             PG8_LDA(At, 0, 1); PG8_STAGE(PG8_SB(0, 0), b2, voffB); PG8_STAGE(PG8_SB(0, 1), b2 + hstep, voffB); PG8_STAGE(PG8_SA(0, 0), a2, voffA);
;             PG8_WAIT_V(8); PG8_WAIT_L(0); PG8_BAR; PG8_MMA(1, 0, At, B0); PG8_MMA(1, 1, At, B1); PG8_BAR; PG8_SCHED;
.LBB0_480:
	s_add_u32 s8, s26, 0x100
	s_addc_u32 s9, s27, 0
	s_add_i32 s54, 0, 0x10000
	s_cmp_eq_u32 s53, 40
	s_cselect_b32 s31, s23, s9
	s_cselect_b32 s30, s22, s8
	s_cselect_b32 s29, s25, s45
	s_cselect_b32 s28, s24, s44
	s_add_i32 s55, 0, 0x14000
	v_add_u32_e32 v100, s54, v234
	v_add_u32_e32 v144, s55, v234
	ds_read_b128 v[68:71], v100
	ds_read_b128 v[80:83], v100 offset:1024
	ds_read_b128 v[92:95], v100 offset:2048
	ds_read_b128 v[100:103], v100 offset:3072
	ds_read_b128 v[112:115], v144
	ds_read_b128 v[120:123], v144 offset:1024
	ds_read_b128 v[132:135], v144 offset:2048
	ds_read_b128 v[144:147], v144 offset:3072
	v_lshl_add_u64 v[198:199], s[26:27], 0, v[204:205]
	s_add_i32 m0, s40, 0xc000
	ds_read_b128 v[156:159], v236
	ds_read_b128 v[168:171], v236 offset:1024
	ds_read_b128 v[172:175], v236 offset:2048
	ds_read_b128 v[176:179], v236 offset:3072
	ds_read_b128 v[180:183], v236 offset:4096
	ds_read_b128 v[184:187], v236 offset:5120
	ds_read_b128 v[188:191], v236 offset:6144
	ds_read_b128 v[208:211], v236 offset:7168
	global_load_lds_dwordx4 v[198:199], off
	s_add_i32 m0, s40, 0xe000
	v_lshl_add_u64 v[198:199], s[26:27], 0, v[206:207]
	global_load_lds_dwordx4 v[198:199], off
	s_waitcnt vmcnt(8) lgkmcnt(0)
	s_barrier
	s_setprio 1
	v_mfma_f32_16x16x32_bf16 v[164:167], v[68:71], v[156:159], v[164:167]
	v_mfma_f32_16x16x32_bf16 v[160:163], v[92:95], v[156:159], v[160:163]
	v_mfma_f32_16x16x32_bf16 v[140:143], v[68:71], v[172:175], v[140:143]
	v_mfma_f32_16x16x32_bf16 v[136:139], v[92:95], v[172:175], v[136:139]
	v_mfma_f32_16x16x32_bf16 v[116:119], v[68:71], v[180:183], v[116:119]
	v_mfma_f32_16x16x32_bf16 v[108:111], v[92:95], v[180:183], v[108:111]
	v_mfma_f32_16x16x32_bf16 v[88:91], v[68:71], v[188:191], v[88:91]
	v_mfma_f32_16x16x32_bf16 v[84:87], v[92:95], v[188:191], v[84:87]
	s_setprio 0
	s_setprio 1
	v_mfma_f32_16x16x32_bf16 v[164:167], v[80:83], v[168:171], v[164:167]
	v_mfma_f32_16x16x32_bf16 v[160:163], v[100:103], v[168:171], v[160:163]
	v_mfma_f32_16x16x32_bf16 v[140:143], v[80:83], v[176:179], v[140:143]
	v_mfma_f32_16x16x32_bf16 v[136:139], v[100:103], v[176:179], v[136:139]
	v_mfma_f32_16x16x32_bf16 v[116:119], v[80:83], v[184:187], v[116:119]
	v_mfma_f32_16x16x32_bf16 v[108:111], v[100:103], v[184:187], v[108:111]
	v_mfma_f32_16x16x32_bf16 v[88:91], v[80:83], v[208:211], v[88:91]
	v_mfma_f32_16x16x32_bf16 v[84:87], v[100:103], v[208:211], v[84:87]
	s_setprio 0
	s_setprio 1
	v_mfma_f32_16x16x32_bf16 v[152:155], v[112:115], v[156:159], v[152:155]
	v_mfma_f32_16x16x32_bf16 v[148:151], v[132:135], v[156:159], v[148:151]
	v_mfma_f32_16x16x32_bf16 v[128:131], v[112:115], v[172:175], v[128:131]
	v_mfma_f32_16x16x32_bf16 v[124:127], v[132:135], v[172:175], v[124:127]
	v_mfma_f32_16x16x32_bf16 v[104:107], v[112:115], v[180:183], v[104:107]
	v_mfma_f32_16x16x32_bf16 v[96:99], v[132:135], v[180:183], v[96:99]
	v_mfma_f32_16x16x32_bf16 v[76:79], v[112:115], v[188:191], v[76:79]
	v_mfma_f32_16x16x32_bf16 v[72:75], v[132:135], v[188:191], v[72:75]
	s_setprio 0
	s_setprio 1
	v_mfma_f32_16x16x32_bf16 v[152:155], v[120:123], v[168:171], v[152:155]
	v_mfma_f32_16x16x32_bf16 v[148:151], v[144:147], v[168:171], v[148:151]
	v_mfma_f32_16x16x32_bf16 v[128:131], v[120:123], v[176:179], v[128:131]
	v_mfma_f32_16x16x32_bf16 v[124:127], v[144:147], v[176:179], v[124:127]
	v_mfma_f32_16x16x32_bf16 v[104:107], v[120:123], v[184:187], v[104:107]
	v_mfma_f32_16x16x32_bf16 v[96:99], v[144:147], v[184:187], v[96:99]
	v_mfma_f32_16x16x32_bf16 v[76:79], v[120:123], v[208:211], v[76:79]
	v_mfma_f32_16x16x32_bf16 v[72:75], v[144:147], v[208:211], v[72:75]
	s_setprio 0
	s_barrier
	s_add_i32 s26, s54, s39
	v_lshl_add_u64 v[198:199], s[28:29], 0, v[192:193]
	s_mov_b32 m0, s26
	ds_read_b128 v[156:159], v236 offset:16384
	ds_read_b128 v[168:171], v236 offset:17408
	ds_read_b128 v[172:175], v236 offset:18432
	ds_read_b128 v[176:179], v236 offset:19456
	ds_read_b128 v[180:183], v236 offset:20480
	ds_read_b128 v[184:187], v236 offset:21504
	ds_read_b128 v[188:191], v236 offset:22528
	ds_read_b128 v[208:211], v236 offset:23552
	global_load_lds_dwordx4 v[198:199], off
	s_add_i32 m0, s26, 0x2000
	s_add_u32 s26, s28, 0xb0000
	v_lshl_add_u64 v[212:213], s[28:29], 0, v[202:203]
	s_addc_u32 s27, s29, 0
	s_add_i32 s54, s55, s39
	global_load_lds_dwordx4 v[212:213], off
	v_lshl_add_u64 v[214:215], s[26:27], 0, v[192:193]
	s_mov_b32 m0, s54
	v_lshl_add_u64 v[216:217], s[30:31], 0, v[194:195]
	global_load_lds_dwordx4 v[214:215], off
	s_add_i32 m0, s54, 0x2000
	v_lshl_add_u64 v[214:215], s[26:27], 0, v[202:203]
	global_load_lds_dwordx4 v[214:215], off
	s_mov_b32 m0, s40
	v_lshl_add_u64 v[214:215], s[30:31], 0, v[0:1]
	global_load_lds_dwordx4 v[214:215], off
	s_mov_b32 m0, s41
	s_add_i32 s54, 0, 0x18000
	global_load_lds_dwordx4 v[216:217], off
	s_waitcnt vmcnt(8) lgkmcnt(0)
	s_barrier
; #define PG8_STAGE(bufoff, gbase, voff) do { _Pragma("unroll") for (int _i = 0; _i < 2; ++_i) \
;         __builtin_amdgcn_global_load_lds((const unsigned*)((const char*)(gbase) + (voff)[_i]), (PG8_LAS unsigned*)(lds + (bufoff) + ldsw + _i * 8192), 16, 0, 0); } while (0)
; #define PG8_LDA(dst, b, h) do { _Pragma("unroll") for (int m = 0; m < 4; ++m) _Pragma("unroll") for (int k = 0; k < 2; ++k) dst[m][k] = *(const PG8_LAS bf16x8*)(lds + PG8_SA(b, h) + aoff + m * 2048 + k * 1024); } while (0)
; #define PG8_LDB(dst, b, h) do { _Pragma("unroll") for (int n = 0; n < 2; ++n) _Pragma("unroll") for (int k = 0; k < 2; ++k) dst[n][k] = *(const PG8_LAS bf16x8*)(lds + PG8_SB(b, h) + boff + n * 2048 + k * 1024); } while (0)
; #define PG8_MMA(ai, bj, At, Bt) do { __builtin_amdgcn_s_setprio(1); _Pragma("unroll") for (int m = 0; m < 4; ++m) _Pragma("unroll") for (int n = 0; n < 2; ++n) _Pragma("unroll") for (int k = 0; k < 2; ++k) \
;         acc[ai][bj][m][n] = __builtin_amdgcn_mfma_f32_16x16x32_bf16(Bt[n][k], At[m][k], acc[ai][bj][m][n], 0, 0, 0); __builtin_amdgcn_s_setprio(0); } while (0)
; #define PG8_WAIT_V(n) asm volatile("s_waitcnt vmcnt(" #n ")" ::: "memory")
; #define PG8_WAIT_L(n) asm volatile("s_waitcnt lgkmcnt(" #n ")" ::: "memory")
; #define PG8_BAR __builtin_amdgcn_s_barrier()
; #define PG8_SCHED __builtin_amdgcn_sched_barrier(0)
; template <class Epi, class Sched, bool ALIGN_EPI = false, bool SP2 = false>
; __device__ __forceinline__ void gemm_phase(PG8_LAS unsigned char* lds, const Gemm g, const Sched& S, const Epi& E) {
;     ...
;             PG8_WAIT_V(8); PG8_WAIT_L(0); PG8_BAR; PG8_MMA(1, 0, At, B0); PG8_MMA(1, 1, At, B1); PG8_BAR; PG8_SCHED;
;             PG8_LDB(B0, 1, 0); PG8_LDB(B1, 1, 1); PG8_SCHED; PG8_LDA(At, 1, 0); PG8_STAGE(PG8_SA(0, 1), a2 + hstep, voffA);
;             PG8_WAIT_V(8); PG8_WAIT_L(0); PG8_BAR; PG8_MMA(0, 0, At, B0); PG8_MMA(0, 1, At, B1); PG8_BAR; PG8_SCHED;
	s_setprio 1
	v_mfma_f32_16x16x32_bf16 v[64:67], v[68:71], v[156:159], v[64:67]
	v_mfma_f32_16x16x32_bf16 v[60:63], v[92:95], v[156:159], v[60:63]
	v_mfma_f32_16x16x32_bf16 v[48:51], v[68:71], v[172:175], v[48:51]
	v_mfma_f32_16x16x32_bf16 v[44:47], v[92:95], v[172:175], v[44:47]
	v_mfma_f32_16x16x32_bf16 v[32:35], v[68:71], v[180:183], v[32:35]
	v_mfma_f32_16x16x32_bf16 v[28:31], v[92:95], v[180:183], v[28:31]
	v_mfma_f32_16x16x32_bf16 v[16:19], v[68:71], v[188:191], v[16:19]
	v_mfma_f32_16x16x32_bf16 v[12:15], v[92:95], v[188:191], v[12:15]
	s_setprio 0
	s_setprio 1
	v_mfma_f32_16x16x32_bf16 v[64:67], v[80:83], v[168:171], v[64:67]
	v_mfma_f32_16x16x32_bf16 v[60:63], v[100:103], v[168:171], v[60:63]
	v_mfma_f32_16x16x32_bf16 v[48:51], v[80:83], v[176:179], v[48:51]
	v_mfma_f32_16x16x32_bf16 v[44:47], v[100:103], v[176:179], v[44:47]
	v_mfma_f32_16x16x32_bf16 v[32:35], v[80:83], v[184:187], v[32:35]
	v_mfma_f32_16x16x32_bf16 v[28:31], v[100:103], v[184:187], v[28:31]
	v_mfma_f32_16x16x32_bf16 v[16:19], v[80:83], v[208:211], v[16:19]
	v_mfma_f32_16x16x32_bf16 v[12:15], v[100:103], v[208:211], v[12:15]
	s_setprio 0
	s_setprio 1
	v_mfma_f32_16x16x32_bf16 v[56:59], v[112:115], v[156:159], v[56:59]
	v_mfma_f32_16x16x32_bf16 v[52:55], v[132:135], v[156:159], v[52:55]
	v_mfma_f32_16x16x32_bf16 v[40:43], v[112:115], v[172:175], v[40:43]
	v_mfma_f32_16x16x32_bf16 v[36:39], v[132:135], v[172:175], v[36:39]
	v_mfma_f32_16x16x32_bf16 v[24:27], v[112:115], v[180:183], v[24:27]
	v_mfma_f32_16x16x32_bf16 v[20:23], v[132:135], v[180:183], v[20:23]
	v_mfma_f32_16x16x32_bf16 v[8:11], v[112:115], v[188:191], v[8:11]
	v_mfma_f32_16x16x32_bf16 v[4:7], v[132:135], v[188:191], v[4:7]
	s_setprio 0
	s_setprio 1
	v_mfma_f32_16x16x32_bf16 v[56:59], v[120:123], v[168:171], v[56:59]
	v_mfma_f32_16x16x32_bf16 v[52:55], v[144:147], v[168:171], v[52:55]
	v_mfma_f32_16x16x32_bf16 v[40:43], v[120:123], v[176:179], v[40:43]
	v_mfma_f32_16x16x32_bf16 v[36:39], v[144:147], v[176:179], v[36:39]
	v_mfma_f32_16x16x32_bf16 v[24:27], v[120:123], v[184:187], v[24:27]
	v_mfma_f32_16x16x32_bf16 v[20:23], v[144:147], v[184:187], v[20:23]
	v_mfma_f32_16x16x32_bf16 v[8:11], v[120:123], v[208:211], v[8:11]
	v_mfma_f32_16x16x32_bf16 v[4:7], v[144:147], v[208:211], v[4:7]
	s_setprio 0
	s_barrier
	s_add_i32 s55, 0, 0x1c000
	v_add_u32_e32 v100, s54, v234
	v_add_u32_e32 v144, s55, v234
	ds_read_b128 v[68:71], v100
	ds_read_b128 v[80:83], v100 offset:1024
	ds_read_b128 v[92:95], v100 offset:2048
	ds_read_b128 v[100:103], v100 offset:3072
	ds_read_b128 v[112:115], v144
	ds_read_b128 v[120:123], v144 offset:1024
	ds_read_b128 v[132:135], v144 offset:2048
	ds_read_b128 v[144:147], v144 offset:3072
	s_add_u32 s26, s30, 0xb0000
	s_addc_u32 s27, s31, 0
	s_mov_b32 m0, s42
	v_lshl_add_u64 v[218:219], s[26:27], 0, v[0:1]
	ds_read_b128 v[156:159], v236 offset:32768
	ds_read_b128 v[168:171], v236 offset:33792
	ds_read_b128 v[172:175], v236 offset:34816
	ds_read_b128 v[176:179], v236 offset:35840
	ds_read_b128 v[180:183], v236 offset:36864
	ds_read_b128 v[184:187], v236 offset:37888
	ds_read_b128 v[188:191], v236 offset:38912
	ds_read_b128 v[208:211], v236 offset:39936
	global_load_lds_dwordx4 v[218:219], off
	s_mov_b32 m0, s43
	v_lshl_add_u64 v[218:219], s[26:27], 0, v[194:195]
	global_load_lds_dwordx4 v[218:219], off
	s_waitcnt vmcnt(8) lgkmcnt(0)
	s_barrier
	s_setprio 1
	v_mfma_f32_16x16x32_bf16 v[164:167], v[68:71], v[156:159], v[164:167]
	v_mfma_f32_16x16x32_bf16 v[160:163], v[92:95], v[156:159], v[160:163]
	v_mfma_f32_16x16x32_bf16 v[140:143], v[68:71], v[172:175], v[140:143]
	v_mfma_f32_16x16x32_bf16 v[136:139], v[92:95], v[172:175], v[136:139]
	v_mfma_f32_16x16x32_bf16 v[116:119], v[68:71], v[180:183], v[116:119]
	v_mfma_f32_16x16x32_bf16 v[108:111], v[92:95], v[180:183], v[108:111]
	v_mfma_f32_16x16x32_bf16 v[88:91], v[68:71], v[188:191], v[88:91]
	v_mfma_f32_16x16x32_bf16 v[84:87], v[92:95], v[188:191], v[84:87]
	s_setprio 0
	s_setprio 1
	v_mfma_f32_16x16x32_bf16 v[164:167], v[80:83], v[168:171], v[164:167]
	v_mfma_f32_16x16x32_bf16 v[160:163], v[100:103], v[168:171], v[160:163]
	v_mfma_f32_16x16x32_bf16 v[140:143], v[80:83], v[176:179], v[140:143]
	v_mfma_f32_16x16x32_bf16 v[136:139], v[100:103], v[176:179], v[136:139]
	v_mfma_f32_16x16x32_bf16 v[116:119], v[80:83], v[184:187], v[116:119]
	v_mfma_f32_16x16x32_bf16 v[108:111], v[100:103], v[184:187], v[108:111]
	v_mfma_f32_16x16x32_bf16 v[88:91], v[80:83], v[208:211], v[88:91]
	v_mfma_f32_16x16x32_bf16 v[84:87], v[100:103], v[208:211], v[84:87]
	s_setprio 0
	s_setprio 1
	v_mfma_f32_16x16x32_bf16 v[152:155], v[112:115], v[156:159], v[152:155]
	v_mfma_f32_16x16x32_bf16 v[148:151], v[132:135], v[156:159], v[148:151]
	v_mfma_f32_16x16x32_bf16 v[128:131], v[112:115], v[172:175], v[128:131]
	v_mfma_f32_16x16x32_bf16 v[124:127], v[132:135], v[172:175], v[124:127]
	v_mfma_f32_16x16x32_bf16 v[104:107], v[112:115], v[180:183], v[104:107]
	v_mfma_f32_16x16x32_bf16 v[96:99], v[132:135], v[180:183], v[96:99]
	v_mfma_f32_16x16x32_bf16 v[76:79], v[112:115], v[188:191], v[76:79]
	v_mfma_f32_16x16x32_bf16 v[72:75], v[132:135], v[188:191], v[72:75]
	s_setprio 0
	s_setprio 1
	v_mfma_f32_16x16x32_bf16 v[152:155], v[120:123], v[168:171], v[152:155]
	v_mfma_f32_16x16x32_bf16 v[148:151], v[144:147], v[168:171], v[148:151]
	v_mfma_f32_16x16x32_bf16 v[128:131], v[120:123], v[176:179], v[128:131]
	v_mfma_f32_16x16x32_bf16 v[124:127], v[144:147], v[176:179], v[124:127]
	v_mfma_f32_16x16x32_bf16 v[104:107], v[120:123], v[184:187], v[104:107]
	v_mfma_f32_16x16x32_bf16 v[96:99], v[144:147], v[184:187], v[96:99]
	v_mfma_f32_16x16x32_bf16 v[76:79], v[120:123], v[208:211], v[76:79]
	v_mfma_f32_16x16x32_bf16 v[72:75], v[144:147], v[208:211], v[72:75]
	s_setprio 0
	s_barrier
; #define PG8_STAGE(bufoff, gbase, voff) do { _Pragma("unroll") for (int _i = 0; _i < 2; ++_i) \
;         __builtin_amdgcn_global_load_lds((const unsigned*)((const char*)(gbase) + (voff)[_i]), (PG8_LAS unsigned*)(lds + (bufoff) + ldsw + _i * 8192), 16, 0, 0); } while (0)
; #define PG8_LDA(dst, b, h) do { _Pragma("unroll") for (int m = 0; m < 4; ++m) _Pragma("unroll") for (int k = 0; k < 2; ++k) dst[m][k] = *(const PG8_LAS bf16x8*)(lds + PG8_SA(b, h) + aoff + m * 2048 + k * 1024); } while (0)
; #define PG8_MMA(ai, bj, At, Bt) do { __builtin_amdgcn_s_setprio(1); _Pragma("unroll") for (int m = 0; m < 4; ++m) _Pragma("unroll") for (int n = 0; n < 2; ++n) _Pragma("unroll") for (int k = 0; k < 2; ++k) \
;         acc[ai][bj][m][n] = __builtin_amdgcn_mfma_f32_16x16x32_bf16(Bt[n][k], At[m][k], acc[ai][bj][m][n], 0, 0, 0); __builtin_amdgcn_s_setprio(0); } while (0)
; #define PG8_WAIT_V(n) asm volatile("s_waitcnt vmcnt(" #n ")" ::: "memory")
; #define PG8_WAIT_L(n) asm volatile("s_waitcnt lgkmcnt(" #n ")" ::: "memory")
; #define PG8_BAR __builtin_amdgcn_s_barrier()
; #define PG8_SCHED __builtin_amdgcn_sched_barrier(0)
; template <class Epi, class Sched, bool ALIGN_EPI = false, bool SP2 = false>
; __device__ __forceinline__ void gemm_phase(PG8_LAS unsigned char* lds, const Gemm g, const Sched& S, const Epi& E) {
;     ...
;             PG8_LDA(At, 1, 1); PG8_STAGE(PG8_SB(1, 0), b3, voffB); PG8_STAGE(PG8_SB(1, 1), b3 + hstep, voffB); PG8_STAGE(PG8_SA(1, 0), a3, voffA);
;             PG8_WAIT_V(8); PG8_WAIT_L(0); PG8_BAR; PG8_MMA(1, 0, At, B0); PG8_MMA(1, 1, At, B1); PG8_BAR; PG8_SCHED;
;     ...
;         if constexpr (ALIGN_EPI) { if (wr == 0) PG8_BAR; }
	s_add_i32 s26, s54, s39
	v_lshl_add_u64 v[198:199], v[198:199], 0, s[82:83]
	s_mov_b32 m0, s26
	ds_read_b128 v[156:159], v236 offset:49152
	ds_read_b128 v[168:171], v236 offset:50176
	ds_read_b128 v[172:175], v236 offset:51200
	ds_read_b128 v[176:179], v236 offset:52224
	ds_read_b128 v[180:183], v236 offset:53248
	ds_read_b128 v[184:187], v236 offset:54272
	ds_read_b128 v[188:191], v236 offset:55296
	ds_read_b128 v[208:211], v236 offset:56320
	global_load_lds_dwordx4 v[198:199], off
	s_add_i32 m0, s26, 0x2000
	s_add_u32 s26, s28, 0xb0080
	v_lshl_add_u64 v[198:199], v[212:213], 0, s[82:83]
	s_addc_u32 s27, s29, 0
	s_add_i32 s28, s55, s39
	global_load_lds_dwordx4 v[198:199], off
	s_mov_b32 m0, s28
	v_lshl_add_u64 v[198:199], s[26:27], 0, v[192:193]
	global_load_lds_dwordx4 v[198:199], off
	s_add_i32 m0, s28, 0x2000
	v_lshl_add_u64 v[198:199], s[26:27], 0, v[202:203]
	global_load_lds_dwordx4 v[198:199], off
	s_mov_b32 m0, s47
	v_lshl_add_u64 v[198:199], v[214:215], 0, s[82:83]
	global_load_lds_dwordx4 v[198:199], off
	s_mov_b32 m0, s48
	v_lshl_add_u64 v[198:199], v[216:217], 0, s[82:83]
	global_load_lds_dwordx4 v[198:199], off
	s_waitcnt vmcnt(8) lgkmcnt(0)
	s_barrier
	s_setprio 1
	v_mfma_f32_16x16x32_bf16 v[64:67], v[68:71], v[156:159], v[64:67]
	v_mfma_f32_16x16x32_bf16 v[60:63], v[92:95], v[156:159], v[60:63]
	v_mfma_f32_16x16x32_bf16 v[48:51], v[68:71], v[172:175], v[48:51]
	v_mfma_f32_16x16x32_bf16 v[44:47], v[92:95], v[172:175], v[44:47]
	v_mfma_f32_16x16x32_bf16 v[32:35], v[68:71], v[180:183], v[32:35]
	v_mfma_f32_16x16x32_bf16 v[28:31], v[92:95], v[180:183], v[28:31]
	v_mfma_f32_16x16x32_bf16 v[16:19], v[68:71], v[188:191], v[16:19]
	v_mfma_f32_16x16x32_bf16 v[12:15], v[92:95], v[188:191], v[12:15]
	s_setprio 0
	s_setprio 1
	v_mfma_f32_16x16x32_bf16 v[64:67], v[80:83], v[168:171], v[64:67]
	v_mfma_f32_16x16x32_bf16 v[60:63], v[100:103], v[168:171], v[60:63]
	v_mfma_f32_16x16x32_bf16 v[48:51], v[80:83], v[176:179], v[48:51]
	v_mfma_f32_16x16x32_bf16 v[44:47], v[100:103], v[176:179], v[44:47]
	v_mfma_f32_16x16x32_bf16 v[32:35], v[80:83], v[184:187], v[32:35]
	v_mfma_f32_16x16x32_bf16 v[28:31], v[100:103], v[184:187], v[28:31]
	v_mfma_f32_16x16x32_bf16 v[16:19], v[80:83], v[208:211], v[16:19]
	v_mfma_f32_16x16x32_bf16 v[12:15], v[100:103], v[208:211], v[12:15]
	s_setprio 0
	s_setprio 1
	v_mfma_f32_16x16x32_bf16 v[56:59], v[112:115], v[156:159], v[56:59]
	v_mfma_f32_16x16x32_bf16 v[52:55], v[132:135], v[156:159], v[52:55]
	v_mfma_f32_16x16x32_bf16 v[40:43], v[112:115], v[172:175], v[40:43]
	v_mfma_f32_16x16x32_bf16 v[36:39], v[132:135], v[172:175], v[36:39]
	v_mfma_f32_16x16x32_bf16 v[24:27], v[112:115], v[180:183], v[24:27]
	v_mfma_f32_16x16x32_bf16 v[20:23], v[132:135], v[180:183], v[20:23]
	v_mfma_f32_16x16x32_bf16 v[8:11], v[112:115], v[188:191], v[8:11]
	v_mfma_f32_16x16x32_bf16 v[4:7], v[132:135], v[188:191], v[4:7]
	s_setprio 0
	s_setprio 1
	v_mfma_f32_16x16x32_bf16 v[56:59], v[120:123], v[168:171], v[56:59]
	v_mfma_f32_16x16x32_bf16 v[52:55], v[144:147], v[168:171], v[52:55]
	v_mfma_f32_16x16x32_bf16 v[40:43], v[120:123], v[176:179], v[40:43]
	v_mfma_f32_16x16x32_bf16 v[36:39], v[144:147], v[176:179], v[36:39]
	v_mfma_f32_16x16x32_bf16 v[24:27], v[120:123], v[184:187], v[24:27]
	v_mfma_f32_16x16x32_bf16 v[20:23], v[144:147], v[184:187], v[20:23]
	v_mfma_f32_16x16x32_bf16 v[8:11], v[120:123], v[208:211], v[8:11]
	v_mfma_f32_16x16x32_bf16 v[4:7], v[144:147], v[208:211], v[4:7]
	s_setprio 0
	s_barrier
	s_add_i32 s53, s53, 2
	s_add_u32 s44, s44, 0x100
	s_addc_u32 s45, s45, 0
	s_cmp_gt_u32 s53, 41
	s_mov_b64 s[26:27], s[8:9]
	s_cbranch_scc0 .LBB0_480
	s_and_b64 vcc, exec, s[20:21]
	s_cbranch_vccz .LBB0_483
	s_barrier
